# P1 and P5 K-loops regenerated with the same hand generator as P4 (SGPR-base loads, deep prefetch, rolling fragment prefetch, interleaved loads and LDS writes)
# speedup vs baseline: 1.1064x; 1.0082x over previous
; DI int TID() { int t = threadIdx.x; asm volatile("" : "+v"(t)); return t; }
; #define GEMM_GLOAD(P, kt_) { GEMM_GL1(P, 0, kt_) GEMM_GL1(P, 1, kt_) GEMM_GL1(P, 2, kt_) GEMM_GL1(P, 3, kt_) }
; #define GEMM_LSTORE(P, buf_) { GEMM_LS1(P, 0, buf_) GEMM_LS1(P, 1, buf_) GEMM_LS1(P, 2, buf_) GEMM_LS1(P, 3, buf_) }
; template <bool DEEP>
; DI void gemm_mainloop_t(const u16* __restrict__ Ag, int lda, const u16* __restrict__ Bg, int ldb, int K, char* ldsraw,
;                         f32x16 (&acc)[2][2], int akstep) {
;   const int tid = TID(), lane = tid & 63, w = tid >> 6, wm = w >> 1, wn = w & 1, r = lane & 31, h = lane >> 5;
;   u16* As = (u16*)ldsraw;
;   u16* Bs = As + 2 * 128 * LDT;
;   uint4 xa0, xa1, xa2, xa3, xb0, xb1, xb2, xb3;
;   const int nk = K >> 6;
;   const int row0 = tid >> 3, cc = tid & 7;
;   if (DEEP) {
;     uint4 ya0, ya1, ya2, ya3, yb0, yb1, yb2, yb3;
;     GEMM_GLOAD(x, 0);
;     GEMM_GLOAD(y, 1);
;     GEMM_LSTORE(x, 0);
;     __syncthreads();
;     for (int kt = 0; kt < nk; kt += 2) {
;       if (kt + 2 < nk) GEMM_GLOAD(x, kt + 2);
;       GEMM_COMPUTE(0);
;       GEMM_LSTORE(y, 1);
;       __syncthreads();
;       if (kt + 3 < nk) GEMM_GLOAD(y, kt + 3);
;       GEMM_COMPUTE(1);
;       if (kt + 2 < nk) GEMM_LSTORE(x, 0);
;       __syncthreads();
; DI void phase1(const Params& p, int l, char* lds) {
;     ...
;   for (int tile = blockIdx.x; tile < 128 * 51; tile += gridDim.x) {
;     const int grp = tile / (32 * 51), rem = tile % (32 * 51);
;     const int nt = rem >> 5, mt = grp * 32 + (rem & 31);
;     f32x16 acc[2][2];
;     zero_acc(acc);
;     gemm_mainloop(p.xn + (size_t)mt * 128 * 1024, 1024, WINT(l) + (size_t)nt * 128 * 1024, 1024, 1024, lds, acc);
.LBB0_219:
	s_mul_hi_i32 s0, s3, 0xa0a0a0a1
	s_add_i32 s0, s0, s3
	s_lshr_b32 s1, s0, 31
	s_ashr_i32 s0, s0, 10
	s_add_i32 s1, s0, s1
	s_mul_i32 s0, s1, 0xfffff9a0
	s_add_i32 s18, s3, s0
	s_lshl_b32 s1, s1, 5
	s_and_b32 s12, s18, 31
	s_or_b32 s12, s1, s12
	s_ashr_i32 s13, s12, 31
	s_ashr_i32 s0, s18, 5
	s_lshl_b64 s[14:15], s[12:13], 18
	s_waitcnt vmcnt(31)
	s_add_u32 s14, s88, s14
	s_addc_u32 s15, s89, s15
	s_ashr_i32 s1, s0, 31
	s_lshl_b64 s[16:17], s[0:1], 18
	s_add_u32 s16, s20, s16
	s_addc_u32 s17, s21, s17
	v_lshrrev_b32_e32 v146, 3, v209
	v_and_b32_e32 v147, 7, v209
	v_lshlrev_b32_e32 v147, 4, v147
	v_mov_b32_e32 v148, v146
	v_mul_u32_u24_e32 v134, 0x800, v148
	v_add_u32_e32 v134, v134, v147
	v_mul_u32_u24_e32 v138, 0x800, v148
	v_add_u32_e32 v138, v138, v147
	v_add_u32_e32 v148, 32, v146
	v_mul_u32_u24_e32 v135, 0x800, v148
	v_add_u32_e32 v135, v135, v147
	v_mul_u32_u24_e32 v139, 0x800, v148
	v_add_u32_e32 v139, v139, v147
	v_add_u32_e32 v148, 64, v146
	v_mul_u32_u24_e32 v136, 0x800, v148
	v_add_u32_e32 v136, v136, v147
	v_mul_u32_u24_e32 v140, 0x800, v148
	v_add_u32_e32 v140, v140, v147
	v_add_u32_e32 v148, 96, v146
	v_mul_u32_u24_e32 v137, 0x800, v148
	v_add_u32_e32 v137, v137, v147
	v_mul_u32_u24_e32 v141, 0x800, v148
	v_add_u32_e32 v141, v141, v147
	v_mul_u32_u24_e32 v142, 0x90, v146
	v_add_u32_e32 v142, v142, v147
	v_add_u32_e32 v143, 0x1200, v142
	v_and_b32_e32 v146, 31, v209
	v_bfe_u32 v147, v209, 5, 1
	v_lshlrev_b32_e32 v147, 4, v147
	v_bfe_u32 v148, v209, 7, 1
	v_lshl_add_u32 v148, v148, 6, v146
	v_mul_u32_u24_e32 v144, 0x90, v148
	v_add_u32_e32 v144, v144, v147
	v_bfe_u32 v148, v209, 6, 1
	v_lshl_add_u32 v148, v148, 6, v146
	v_mul_u32_u24_e32 v145, 0x90, v148
	v_add_u32_e32 v145, v145, v147
	global_load_dwordx4 v[66:69], v134, s[14:15]
	global_load_dwordx4 v[70:73], v138, s[16:17]
	global_load_dwordx4 v[74:77], v135, s[14:15]
	global_load_dwordx4 v[78:81], v139, s[16:17]
	global_load_dwordx4 v[82:85], v136, s[14:15]
	global_load_dwordx4 v[86:89], v140, s[16:17]
	global_load_dwordx4 v[90:93], v137, s[14:15]
	global_load_dwordx4 v[94:97], v141, s[16:17]
	global_load_dwordx4 v[98:101], v134, s[14:15] offset:128
	global_load_dwordx4 v[102:105], v138, s[16:17] offset:128
	global_load_dwordx4 v[106:109], v135, s[14:15] offset:128
	global_load_dwordx4 v[110:113], v139, s[16:17] offset:128
	global_load_dwordx4 v[114:117], v136, s[14:15] offset:128
	global_load_dwordx4 v[118:121], v140, s[16:17] offset:128
	global_load_dwordx4 v[122:125], v137, s[14:15] offset:128
	global_load_dwordx4 v[126:129], v141, s[16:17] offset:128
	s_waitcnt vmcnt(15)
	ds_write_b128 v142, v[66:69]
	s_waitcnt vmcnt(14)
	ds_write_b128 v142, v[70:73] offset:36864
	s_waitcnt vmcnt(13)
	ds_write_b128 v142, v[74:77] offset:4608
	s_waitcnt vmcnt(12)
	ds_write_b128 v142, v[78:81] offset:41472
	s_waitcnt vmcnt(11)
	ds_write_b128 v142, v[82:85] offset:9216
	s_waitcnt vmcnt(10)
	ds_write_b128 v142, v[86:89] offset:46080
	s_waitcnt vmcnt(9)
	ds_write_b128 v142, v[90:93] offset:13824
	s_waitcnt vmcnt(8)
	ds_write_b128 v142, v[94:97] offset:50688
	s_waitcnt lgkmcnt(0)
	s_barrier
	s_setprio 1
	ds_read_b128 v[156:159], v145 offset:36864
	ds_read_b128 v[160:163], v144
	ds_read_b128 v[164:167], v145 offset:41472
	ds_read_b128 v[168:171], v144 offset:4608
	s_waitcnt lgkmcnt(2)
	v_mfma_f32_32x32x16_f16 v[50:65], v[156:159], v[160:163], 0
	global_load_dwordx4 v[66:69], v134, s[14:15] offset:256
	s_waitcnt lgkmcnt(1)
	v_mfma_f32_32x32x16_f16 v[34:49], v[164:167], v[160:163], 0
	ds_read_b128 v[160:163], v144 offset:32
	s_waitcnt vmcnt(8)
	ds_write_b128 v142, v[98:101] offset:18432
	s_waitcnt lgkmcnt(2)
	v_mfma_f32_32x32x16_f16 v[18:33], v[156:159], v[168:171], 0
	ds_read_b128 v[156:159], v145 offset:36896
	global_load_dwordx4 v[70:73], v138, s[16:17] offset:256
	v_mfma_f32_32x32x16_f16 v[2:17], v[164:167], v[168:171], 0
	ds_read_b128 v[164:167], v145 offset:41504
	ds_read_b128 v[168:171], v144 offset:4640
	s_waitcnt vmcnt(8)
	ds_write_b128 v142, v[102:105] offset:55296
	s_waitcnt lgkmcnt(3)
	v_mfma_f32_32x32x16_f16 v[50:65], v[156:159], v[160:163], v[50:65]
	global_load_dwordx4 v[74:77], v135, s[14:15] offset:256
	s_waitcnt lgkmcnt(2)
	v_mfma_f32_32x32x16_f16 v[34:49], v[164:167], v[160:163], v[34:49]
	ds_read_b128 v[160:163], v144 offset:64
	s_waitcnt vmcnt(8)
	ds_write_b128 v142, v[106:109] offset:23040
	s_waitcnt lgkmcnt(3)
	v_mfma_f32_32x32x16_f16 v[18:33], v[156:159], v[168:171], v[18:33]
	ds_read_b128 v[156:159], v145 offset:36928
	global_load_dwordx4 v[78:81], v139, s[16:17] offset:256
	v_mfma_f32_32x32x16_f16 v[2:17], v[164:167], v[168:171], v[2:17]
	ds_read_b128 v[164:167], v145 offset:41536
	ds_read_b128 v[168:171], v144 offset:4672
	s_waitcnt vmcnt(8)
	ds_write_b128 v142, v[110:113] offset:59904
	s_waitcnt lgkmcnt(3)
	v_mfma_f32_32x32x16_f16 v[50:65], v[156:159], v[160:163], v[50:65]
	global_load_dwordx4 v[82:85], v136, s[14:15] offset:256
	s_waitcnt lgkmcnt(2)
	v_mfma_f32_32x32x16_f16 v[34:49], v[164:167], v[160:163], v[34:49]
	ds_read_b128 v[160:163], v144 offset:96
	s_waitcnt vmcnt(8)
	ds_write_b128 v142, v[114:117] offset:27648
	s_waitcnt lgkmcnt(3)
	v_mfma_f32_32x32x16_f16 v[18:33], v[156:159], v[168:171], v[18:33]
	ds_read_b128 v[156:159], v145 offset:36960
	global_load_dwordx4 v[86:89], v140, s[16:17] offset:256
	v_mfma_f32_32x32x16_f16 v[2:17], v[164:167], v[168:171], v[2:17]
	ds_read_b128 v[164:167], v145 offset:41568
	ds_read_b128 v[168:171], v144 offset:4704
	s_waitcnt vmcnt(8)
	ds_write_b128 v142, v[118:121] offset:64512
	s_waitcnt lgkmcnt(3)
	v_mfma_f32_32x32x16_f16 v[50:65], v[156:159], v[160:163], v[50:65]
	global_load_dwordx4 v[90:93], v137, s[14:15] offset:256
	s_waitcnt lgkmcnt(2)
	v_mfma_f32_32x32x16_f16 v[34:49], v[164:167], v[160:163], v[34:49]
	s_waitcnt vmcnt(8)
	ds_write_b128 v142, v[122:125] offset:32256
	s_waitcnt lgkmcnt(2)
	v_mfma_f32_32x32x16_f16 v[18:33], v[156:159], v[168:171], v[18:33]
	global_load_dwordx4 v[94:97], v141, s[16:17] offset:256
	v_mfma_f32_32x32x16_f16 v[2:17], v[164:167], v[168:171], v[2:17]
	s_waitcnt vmcnt(8)
	ds_write_b128 v143, v[126:129] offset:64512
	s_setprio 0
	s_waitcnt lgkmcnt(0)
	s_barrier
; #define GEMM_GLOAD(P, kt_) { GEMM_GL1(P, 0, kt_) GEMM_GL1(P, 1, kt_) GEMM_GL1(P, 2, kt_) GEMM_GL1(P, 3, kt_) }
; #define GEMM_LSTORE(P, buf_) { GEMM_LS1(P, 0, buf_) GEMM_LS1(P, 1, buf_) GEMM_LS1(P, 2, buf_) GEMM_LS1(P, 3, buf_) }
; template <bool DEEP>
; DI void gemm_mainloop_t(const u16* __restrict__ Ag, int lda, const u16* __restrict__ Bg, int ldb, int K, char* ldsraw,
;                         f32x16 (&acc)[2][2], int akstep) {
;     ...
;     for (int kt = 0; kt < nk; kt += 2) {
;       if (kt + 2 < nk) GEMM_GLOAD(x, kt + 2);
;       GEMM_COMPUTE(0);
;       GEMM_LSTORE(y, 1);
;       __syncthreads();
;       if (kt + 3 < nk) GEMM_GLOAD(y, kt + 3);
;       GEMM_COMPUTE(1);
;       if (kt + 2 < nk) GEMM_LSTORE(x, 0);
;       __syncthreads();
	s_setprio 1
	ds_read_b128 v[156:159], v145 offset:55296
	ds_read_b128 v[160:163], v144 offset:18432
	ds_read_b128 v[164:167], v145 offset:59904
	ds_read_b128 v[168:171], v144 offset:23040
	s_waitcnt lgkmcnt(2)
	v_mfma_f32_32x32x16_f16 v[50:65], v[156:159], v[160:163], v[50:65]
	global_load_dwordx4 v[98:101], v134, s[14:15] offset:384
	s_waitcnt lgkmcnt(1)
	v_mfma_f32_32x32x16_f16 v[34:49], v[164:167], v[160:163], v[34:49]
	ds_read_b128 v[160:163], v144 offset:18464
	s_waitcnt vmcnt(8)
	ds_write_b128 v142, v[66:69]
	s_waitcnt lgkmcnt(2)
	v_mfma_f32_32x32x16_f16 v[18:33], v[156:159], v[168:171], v[18:33]
	ds_read_b128 v[156:159], v145 offset:55328
	global_load_dwordx4 v[102:105], v138, s[16:17] offset:384
	v_mfma_f32_32x32x16_f16 v[2:17], v[164:167], v[168:171], v[2:17]
	ds_read_b128 v[164:167], v145 offset:59936
	ds_read_b128 v[168:171], v144 offset:23072
	s_waitcnt vmcnt(8)
	ds_write_b128 v142, v[70:73] offset:36864
	s_waitcnt lgkmcnt(3)
	v_mfma_f32_32x32x16_f16 v[50:65], v[156:159], v[160:163], v[50:65]
	global_load_dwordx4 v[106:109], v135, s[14:15] offset:384
	s_waitcnt lgkmcnt(2)
	v_mfma_f32_32x32x16_f16 v[34:49], v[164:167], v[160:163], v[34:49]
	ds_read_b128 v[160:163], v144 offset:18496
	s_waitcnt vmcnt(8)
	ds_write_b128 v142, v[74:77] offset:4608
	s_waitcnt lgkmcnt(3)
	v_mfma_f32_32x32x16_f16 v[18:33], v[156:159], v[168:171], v[18:33]
	ds_read_b128 v[156:159], v145 offset:55360
	global_load_dwordx4 v[110:113], v139, s[16:17] offset:384
	v_mfma_f32_32x32x16_f16 v[2:17], v[164:167], v[168:171], v[2:17]
	ds_read_b128 v[164:167], v145 offset:59968
	ds_read_b128 v[168:171], v144 offset:23104
	s_waitcnt vmcnt(8)
	ds_write_b128 v142, v[78:81] offset:41472
	s_waitcnt lgkmcnt(3)
	v_mfma_f32_32x32x16_f16 v[50:65], v[156:159], v[160:163], v[50:65]
	global_load_dwordx4 v[114:117], v136, s[14:15] offset:384
	s_waitcnt lgkmcnt(2)
	v_mfma_f32_32x32x16_f16 v[34:49], v[164:167], v[160:163], v[34:49]
	ds_read_b128 v[160:163], v144 offset:18528
	s_waitcnt vmcnt(8)
	ds_write_b128 v142, v[82:85] offset:9216
	s_waitcnt lgkmcnt(3)
	v_mfma_f32_32x32x16_f16 v[18:33], v[156:159], v[168:171], v[18:33]
	ds_read_b128 v[156:159], v145 offset:55392
	global_load_dwordx4 v[118:121], v140, s[16:17] offset:384
	v_mfma_f32_32x32x16_f16 v[2:17], v[164:167], v[168:171], v[2:17]
	ds_read_b128 v[164:167], v145 offset:60000
	ds_read_b128 v[168:171], v144 offset:23136
	s_waitcnt vmcnt(8)
	ds_write_b128 v142, v[86:89] offset:46080
	s_waitcnt lgkmcnt(3)
	v_mfma_f32_32x32x16_f16 v[50:65], v[156:159], v[160:163], v[50:65]
	global_load_dwordx4 v[122:125], v137, s[14:15] offset:384
	s_waitcnt lgkmcnt(2)
	v_mfma_f32_32x32x16_f16 v[34:49], v[164:167], v[160:163], v[34:49]
	s_waitcnt vmcnt(8)
	ds_write_b128 v142, v[90:93] offset:13824
	s_waitcnt lgkmcnt(2)
	v_mfma_f32_32x32x16_f16 v[18:33], v[156:159], v[168:171], v[18:33]
	global_load_dwordx4 v[126:129], v141, s[16:17] offset:384
	v_mfma_f32_32x32x16_f16 v[2:17], v[164:167], v[168:171], v[2:17]
	s_waitcnt vmcnt(8)
	ds_write_b128 v142, v[94:97] offset:50688
	s_setprio 0
	s_waitcnt lgkmcnt(0)
	s_barrier
	s_setprio 1
	ds_read_b128 v[156:159], v145 offset:36864
	ds_read_b128 v[160:163], v144
	ds_read_b128 v[164:167], v145 offset:41472
	ds_read_b128 v[168:171], v144 offset:4608
	s_waitcnt lgkmcnt(2)
	v_mfma_f32_32x32x16_f16 v[50:65], v[156:159], v[160:163], v[50:65]
	global_load_dwordx4 v[66:69], v134, s[14:15] offset:512
	s_waitcnt lgkmcnt(1)
	v_mfma_f32_32x32x16_f16 v[34:49], v[164:167], v[160:163], v[34:49]
	ds_read_b128 v[160:163], v144 offset:32
	s_waitcnt vmcnt(8)
	ds_write_b128 v142, v[98:101] offset:18432
	s_waitcnt lgkmcnt(2)
	v_mfma_f32_32x32x16_f16 v[18:33], v[156:159], v[168:171], v[18:33]
	ds_read_b128 v[156:159], v145 offset:36896
	global_load_dwordx4 v[70:73], v138, s[16:17] offset:512
	v_mfma_f32_32x32x16_f16 v[2:17], v[164:167], v[168:171], v[2:17]
	ds_read_b128 v[164:167], v145 offset:41504
	ds_read_b128 v[168:171], v144 offset:4640
	s_waitcnt vmcnt(8)
	ds_write_b128 v142, v[102:105] offset:55296
	s_waitcnt lgkmcnt(3)
	v_mfma_f32_32x32x16_f16 v[50:65], v[156:159], v[160:163], v[50:65]
	global_load_dwordx4 v[74:77], v135, s[14:15] offset:512
	s_waitcnt lgkmcnt(2)
	v_mfma_f32_32x32x16_f16 v[34:49], v[164:167], v[160:163], v[34:49]
	ds_read_b128 v[160:163], v144 offset:64
	s_waitcnt vmcnt(8)
	ds_write_b128 v142, v[106:109] offset:23040
	s_waitcnt lgkmcnt(3)
	v_mfma_f32_32x32x16_f16 v[18:33], v[156:159], v[168:171], v[18:33]
	ds_read_b128 v[156:159], v145 offset:36928
	global_load_dwordx4 v[78:81], v139, s[16:17] offset:512
	v_mfma_f32_32x32x16_f16 v[2:17], v[164:167], v[168:171], v[2:17]
	ds_read_b128 v[164:167], v145 offset:41536
	ds_read_b128 v[168:171], v144 offset:4672
	s_waitcnt vmcnt(8)
	ds_write_b128 v142, v[110:113] offset:59904
	s_waitcnt lgkmcnt(3)
	v_mfma_f32_32x32x16_f16 v[50:65], v[156:159], v[160:163], v[50:65]
	global_load_dwordx4 v[82:85], v136, s[14:15] offset:512
	s_waitcnt lgkmcnt(2)
	v_mfma_f32_32x32x16_f16 v[34:49], v[164:167], v[160:163], v[34:49]
	ds_read_b128 v[160:163], v144 offset:96
	s_waitcnt vmcnt(8)
	ds_write_b128 v142, v[114:117] offset:27648
	s_waitcnt lgkmcnt(3)
	v_mfma_f32_32x32x16_f16 v[18:33], v[156:159], v[168:171], v[18:33]
	ds_read_b128 v[156:159], v145 offset:36960
	global_load_dwordx4 v[86:89], v140, s[16:17] offset:512
	v_mfma_f32_32x32x16_f16 v[2:17], v[164:167], v[168:171], v[2:17]
	ds_read_b128 v[164:167], v145 offset:41568
	ds_read_b128 v[168:171], v144 offset:4704
	s_waitcnt vmcnt(8)
	ds_write_b128 v142, v[118:121] offset:64512
	s_waitcnt lgkmcnt(3)
	v_mfma_f32_32x32x16_f16 v[50:65], v[156:159], v[160:163], v[50:65]
	global_load_dwordx4 v[90:93], v137, s[14:15] offset:512
	s_waitcnt lgkmcnt(2)
	v_mfma_f32_32x32x16_f16 v[34:49], v[164:167], v[160:163], v[34:49]
	s_waitcnt vmcnt(8)
	ds_write_b128 v142, v[122:125] offset:32256
	s_waitcnt lgkmcnt(2)
	v_mfma_f32_32x32x16_f16 v[18:33], v[156:159], v[168:171], v[18:33]
	global_load_dwordx4 v[94:97], v141, s[16:17] offset:512
	v_mfma_f32_32x32x16_f16 v[2:17], v[164:167], v[168:171], v[2:17]
	s_waitcnt vmcnt(8)
	ds_write_b128 v143, v[126:129] offset:64512
	s_setprio 0
	s_waitcnt lgkmcnt(0)
	s_barrier
; #define GEMM_GLOAD(P, kt_) { GEMM_GL1(P, 0, kt_) GEMM_GL1(P, 1, kt_) GEMM_GL1(P, 2, kt_) GEMM_GL1(P, 3, kt_) }
; #define GEMM_LSTORE(P, buf_) { GEMM_LS1(P, 0, buf_) GEMM_LS1(P, 1, buf_) GEMM_LS1(P, 2, buf_) GEMM_LS1(P, 3, buf_) }
; template <bool DEEP>
; DI void gemm_mainloop_t(const u16* __restrict__ Ag, int lda, const u16* __restrict__ Bg, int ldb, int K, char* ldsraw,
;                         f32x16 (&acc)[2][2], int akstep) {
;     ...
;     for (int kt = 0; kt < nk; kt += 2) {
;       if (kt + 2 < nk) GEMM_GLOAD(x, kt + 2);
;       GEMM_COMPUTE(0);
;       GEMM_LSTORE(y, 1);
;       __syncthreads();
;       if (kt + 3 < nk) GEMM_GLOAD(y, kt + 3);
;       GEMM_COMPUTE(1);
;       if (kt + 2 < nk) GEMM_LSTORE(x, 0);
;       __syncthreads();
	s_setprio 1
	ds_read_b128 v[156:159], v145 offset:55296
	ds_read_b128 v[160:163], v144 offset:18432
	ds_read_b128 v[164:167], v145 offset:59904
	ds_read_b128 v[168:171], v144 offset:23040
	s_waitcnt lgkmcnt(2)
	v_mfma_f32_32x32x16_f16 v[50:65], v[156:159], v[160:163], v[50:65]
	global_load_dwordx4 v[98:101], v134, s[14:15] offset:640
	s_waitcnt lgkmcnt(1)
	v_mfma_f32_32x32x16_f16 v[34:49], v[164:167], v[160:163], v[34:49]
	ds_read_b128 v[160:163], v144 offset:18464
	s_waitcnt vmcnt(8)
	ds_write_b128 v142, v[66:69]
	s_waitcnt lgkmcnt(2)
	v_mfma_f32_32x32x16_f16 v[18:33], v[156:159], v[168:171], v[18:33]
	ds_read_b128 v[156:159], v145 offset:55328
	global_load_dwordx4 v[102:105], v138, s[16:17] offset:640
	v_mfma_f32_32x32x16_f16 v[2:17], v[164:167], v[168:171], v[2:17]
	ds_read_b128 v[164:167], v145 offset:59936
	ds_read_b128 v[168:171], v144 offset:23072
	s_waitcnt vmcnt(8)
	ds_write_b128 v142, v[70:73] offset:36864
	s_waitcnt lgkmcnt(3)
	v_mfma_f32_32x32x16_f16 v[50:65], v[156:159], v[160:163], v[50:65]
	global_load_dwordx4 v[106:109], v135, s[14:15] offset:640
	s_waitcnt lgkmcnt(2)
	v_mfma_f32_32x32x16_f16 v[34:49], v[164:167], v[160:163], v[34:49]
	ds_read_b128 v[160:163], v144 offset:18496
	s_waitcnt vmcnt(8)
	ds_write_b128 v142, v[74:77] offset:4608
	s_waitcnt lgkmcnt(3)
	v_mfma_f32_32x32x16_f16 v[18:33], v[156:159], v[168:171], v[18:33]
	ds_read_b128 v[156:159], v145 offset:55360
	global_load_dwordx4 v[110:113], v139, s[16:17] offset:640
	v_mfma_f32_32x32x16_f16 v[2:17], v[164:167], v[168:171], v[2:17]
	ds_read_b128 v[164:167], v145 offset:59968
	ds_read_b128 v[168:171], v144 offset:23104
	s_waitcnt vmcnt(8)
	ds_write_b128 v142, v[78:81] offset:41472
	s_waitcnt lgkmcnt(3)
	v_mfma_f32_32x32x16_f16 v[50:65], v[156:159], v[160:163], v[50:65]
	global_load_dwordx4 v[114:117], v136, s[14:15] offset:640
	s_waitcnt lgkmcnt(2)
	v_mfma_f32_32x32x16_f16 v[34:49], v[164:167], v[160:163], v[34:49]
	ds_read_b128 v[160:163], v144 offset:18528
	s_waitcnt vmcnt(8)
	ds_write_b128 v142, v[82:85] offset:9216
	s_waitcnt lgkmcnt(3)
	v_mfma_f32_32x32x16_f16 v[18:33], v[156:159], v[168:171], v[18:33]
	ds_read_b128 v[156:159], v145 offset:55392
	global_load_dwordx4 v[118:121], v140, s[16:17] offset:640
	v_mfma_f32_32x32x16_f16 v[2:17], v[164:167], v[168:171], v[2:17]
	ds_read_b128 v[164:167], v145 offset:60000
	ds_read_b128 v[168:171], v144 offset:23136
	s_waitcnt vmcnt(8)
	ds_write_b128 v142, v[86:89] offset:46080
	s_waitcnt lgkmcnt(3)
	v_mfma_f32_32x32x16_f16 v[50:65], v[156:159], v[160:163], v[50:65]
	global_load_dwordx4 v[122:125], v137, s[14:15] offset:640
	s_waitcnt lgkmcnt(2)
	v_mfma_f32_32x32x16_f16 v[34:49], v[164:167], v[160:163], v[34:49]
	s_waitcnt vmcnt(8)
	ds_write_b128 v142, v[90:93] offset:13824
	s_waitcnt lgkmcnt(2)
	v_mfma_f32_32x32x16_f16 v[18:33], v[156:159], v[168:171], v[18:33]
	global_load_dwordx4 v[126:129], v141, s[16:17] offset:640
	v_mfma_f32_32x32x16_f16 v[2:17], v[164:167], v[168:171], v[2:17]
	s_waitcnt vmcnt(8)
	ds_write_b128 v142, v[94:97] offset:50688
	s_setprio 0
	s_waitcnt lgkmcnt(0)
	s_barrier
	s_setprio 1
	ds_read_b128 v[156:159], v145 offset:36864
	ds_read_b128 v[160:163], v144
	ds_read_b128 v[164:167], v145 offset:41472
	ds_read_b128 v[168:171], v144 offset:4608
	s_waitcnt lgkmcnt(2)
	v_mfma_f32_32x32x16_f16 v[50:65], v[156:159], v[160:163], v[50:65]
	global_load_dwordx4 v[66:69], v134, s[14:15] offset:768
	s_waitcnt lgkmcnt(1)
	v_mfma_f32_32x32x16_f16 v[34:49], v[164:167], v[160:163], v[34:49]
	ds_read_b128 v[160:163], v144 offset:32
	s_waitcnt vmcnt(8)
	ds_write_b128 v142, v[98:101] offset:18432
	s_waitcnt lgkmcnt(2)
	v_mfma_f32_32x32x16_f16 v[18:33], v[156:159], v[168:171], v[18:33]
	ds_read_b128 v[156:159], v145 offset:36896
	global_load_dwordx4 v[70:73], v138, s[16:17] offset:768
	v_mfma_f32_32x32x16_f16 v[2:17], v[164:167], v[168:171], v[2:17]
	ds_read_b128 v[164:167], v145 offset:41504
	ds_read_b128 v[168:171], v144 offset:4640
	s_waitcnt vmcnt(8)
	ds_write_b128 v142, v[102:105] offset:55296
	s_waitcnt lgkmcnt(3)
	v_mfma_f32_32x32x16_f16 v[50:65], v[156:159], v[160:163], v[50:65]
	global_load_dwordx4 v[74:77], v135, s[14:15] offset:768
	s_waitcnt lgkmcnt(2)
	v_mfma_f32_32x32x16_f16 v[34:49], v[164:167], v[160:163], v[34:49]
	ds_read_b128 v[160:163], v144 offset:64
	s_waitcnt vmcnt(8)
	ds_write_b128 v142, v[106:109] offset:23040
	s_waitcnt lgkmcnt(3)
	v_mfma_f32_32x32x16_f16 v[18:33], v[156:159], v[168:171], v[18:33]
	ds_read_b128 v[156:159], v145 offset:36928
	global_load_dwordx4 v[78:81], v139, s[16:17] offset:768
	v_mfma_f32_32x32x16_f16 v[2:17], v[164:167], v[168:171], v[2:17]
	ds_read_b128 v[164:167], v145 offset:41536
	ds_read_b128 v[168:171], v144 offset:4672
	s_waitcnt vmcnt(8)
	ds_write_b128 v142, v[110:113] offset:59904
	s_waitcnt lgkmcnt(3)
	v_mfma_f32_32x32x16_f16 v[50:65], v[156:159], v[160:163], v[50:65]
	global_load_dwordx4 v[82:85], v136, s[14:15] offset:768
	s_waitcnt lgkmcnt(2)
	v_mfma_f32_32x32x16_f16 v[34:49], v[164:167], v[160:163], v[34:49]
	ds_read_b128 v[160:163], v144 offset:96
	s_waitcnt vmcnt(8)
	ds_write_b128 v142, v[114:117] offset:27648
	s_waitcnt lgkmcnt(3)
	v_mfma_f32_32x32x16_f16 v[18:33], v[156:159], v[168:171], v[18:33]
	ds_read_b128 v[156:159], v145 offset:36960
	global_load_dwordx4 v[86:89], v140, s[16:17] offset:768
	v_mfma_f32_32x32x16_f16 v[2:17], v[164:167], v[168:171], v[2:17]
	ds_read_b128 v[164:167], v145 offset:41568
	ds_read_b128 v[168:171], v144 offset:4704
	s_waitcnt vmcnt(8)
	ds_write_b128 v142, v[118:121] offset:64512
	s_waitcnt lgkmcnt(3)
	v_mfma_f32_32x32x16_f16 v[50:65], v[156:159], v[160:163], v[50:65]
	global_load_dwordx4 v[90:93], v137, s[14:15] offset:768
	s_waitcnt lgkmcnt(2)
	v_mfma_f32_32x32x16_f16 v[34:49], v[164:167], v[160:163], v[34:49]
	s_waitcnt vmcnt(8)
	ds_write_b128 v142, v[122:125] offset:32256
	s_waitcnt lgkmcnt(2)
	v_mfma_f32_32x32x16_f16 v[18:33], v[156:159], v[168:171], v[18:33]
	global_load_dwordx4 v[94:97], v141, s[16:17] offset:768
	v_mfma_f32_32x32x16_f16 v[2:17], v[164:167], v[168:171], v[2:17]
	s_waitcnt vmcnt(8)
	ds_write_b128 v143, v[126:129] offset:64512
	s_setprio 0
	s_waitcnt lgkmcnt(0)
	s_barrier
; #define GEMM_GLOAD(P, kt_) { GEMM_GL1(P, 0, kt_) GEMM_GL1(P, 1, kt_) GEMM_GL1(P, 2, kt_) GEMM_GL1(P, 3, kt_) }
; #define GEMM_LSTORE(P, buf_) { GEMM_LS1(P, 0, buf_) GEMM_LS1(P, 1, buf_) GEMM_LS1(P, 2, buf_) GEMM_LS1(P, 3, buf_) }
; template <bool DEEP>
; DI void gemm_mainloop_t(const u16* __restrict__ Ag, int lda, const u16* __restrict__ Bg, int ldb, int K, char* ldsraw,
;                         f32x16 (&acc)[2][2], int akstep) {
;     ...
;     for (int kt = 0; kt < nk; kt += 2) {
;       if (kt + 2 < nk) GEMM_GLOAD(x, kt + 2);
;       GEMM_COMPUTE(0);
;       GEMM_LSTORE(y, 1);
;       __syncthreads();
;       if (kt + 3 < nk) GEMM_GLOAD(y, kt + 3);
;       GEMM_COMPUTE(1);
;       if (kt + 2 < nk) GEMM_LSTORE(x, 0);
;       __syncthreads();
	s_setprio 1
	ds_read_b128 v[156:159], v145 offset:55296
	ds_read_b128 v[160:163], v144 offset:18432
	ds_read_b128 v[164:167], v145 offset:59904
	ds_read_b128 v[168:171], v144 offset:23040
	s_waitcnt lgkmcnt(2)
	v_mfma_f32_32x32x16_f16 v[50:65], v[156:159], v[160:163], v[50:65]
	global_load_dwordx4 v[98:101], v134, s[14:15] offset:896
	s_waitcnt lgkmcnt(1)
	v_mfma_f32_32x32x16_f16 v[34:49], v[164:167], v[160:163], v[34:49]
	ds_read_b128 v[160:163], v144 offset:18464
	s_waitcnt vmcnt(8)
	ds_write_b128 v142, v[66:69]
	s_waitcnt lgkmcnt(2)
	v_mfma_f32_32x32x16_f16 v[18:33], v[156:159], v[168:171], v[18:33]
	ds_read_b128 v[156:159], v145 offset:55328
	global_load_dwordx4 v[102:105], v138, s[16:17] offset:896
	v_mfma_f32_32x32x16_f16 v[2:17], v[164:167], v[168:171], v[2:17]
	ds_read_b128 v[164:167], v145 offset:59936
	ds_read_b128 v[168:171], v144 offset:23072
	s_waitcnt vmcnt(8)
	ds_write_b128 v142, v[70:73] offset:36864
	s_waitcnt lgkmcnt(3)
	v_mfma_f32_32x32x16_f16 v[50:65], v[156:159], v[160:163], v[50:65]
	global_load_dwordx4 v[106:109], v135, s[14:15] offset:896
	s_waitcnt lgkmcnt(2)
	v_mfma_f32_32x32x16_f16 v[34:49], v[164:167], v[160:163], v[34:49]
	ds_read_b128 v[160:163], v144 offset:18496
	s_waitcnt vmcnt(8)
	ds_write_b128 v142, v[74:77] offset:4608
	s_waitcnt lgkmcnt(3)
	v_mfma_f32_32x32x16_f16 v[18:33], v[156:159], v[168:171], v[18:33]
	ds_read_b128 v[156:159], v145 offset:55360
	global_load_dwordx4 v[110:113], v139, s[16:17] offset:896
	v_mfma_f32_32x32x16_f16 v[2:17], v[164:167], v[168:171], v[2:17]
	ds_read_b128 v[164:167], v145 offset:59968
	ds_read_b128 v[168:171], v144 offset:23104
	s_waitcnt vmcnt(8)
	ds_write_b128 v142, v[78:81] offset:41472
	s_waitcnt lgkmcnt(3)
	v_mfma_f32_32x32x16_f16 v[50:65], v[156:159], v[160:163], v[50:65]
	global_load_dwordx4 v[114:117], v136, s[14:15] offset:896
	s_waitcnt lgkmcnt(2)
	v_mfma_f32_32x32x16_f16 v[34:49], v[164:167], v[160:163], v[34:49]
	ds_read_b128 v[160:163], v144 offset:18528
	s_waitcnt vmcnt(8)
	ds_write_b128 v142, v[82:85] offset:9216
	s_waitcnt lgkmcnt(3)
	v_mfma_f32_32x32x16_f16 v[18:33], v[156:159], v[168:171], v[18:33]
	ds_read_b128 v[156:159], v145 offset:55392
	global_load_dwordx4 v[118:121], v140, s[16:17] offset:896
	v_mfma_f32_32x32x16_f16 v[2:17], v[164:167], v[168:171], v[2:17]
	ds_read_b128 v[164:167], v145 offset:60000
	ds_read_b128 v[168:171], v144 offset:23136
	s_waitcnt vmcnt(8)
	ds_write_b128 v142, v[86:89] offset:46080
	s_waitcnt lgkmcnt(3)
	v_mfma_f32_32x32x16_f16 v[50:65], v[156:159], v[160:163], v[50:65]
	global_load_dwordx4 v[122:125], v137, s[14:15] offset:896
	s_waitcnt lgkmcnt(2)
	v_mfma_f32_32x32x16_f16 v[34:49], v[164:167], v[160:163], v[34:49]
	s_waitcnt vmcnt(8)
	ds_write_b128 v142, v[90:93] offset:13824
	s_waitcnt lgkmcnt(2)
	v_mfma_f32_32x32x16_f16 v[18:33], v[156:159], v[168:171], v[18:33]
	global_load_dwordx4 v[126:129], v141, s[16:17] offset:896
	v_mfma_f32_32x32x16_f16 v[2:17], v[164:167], v[168:171], v[2:17]
	s_waitcnt vmcnt(8)
	ds_write_b128 v142, v[94:97] offset:50688
	s_setprio 0
	s_waitcnt lgkmcnt(0)
	s_barrier
	s_setprio 1
	ds_read_b128 v[156:159], v145 offset:36864
	ds_read_b128 v[160:163], v144
	ds_read_b128 v[164:167], v145 offset:41472
	ds_read_b128 v[168:171], v144 offset:4608
	s_waitcnt lgkmcnt(2)
	v_mfma_f32_32x32x16_f16 v[50:65], v[156:159], v[160:163], v[50:65]
	global_load_dwordx4 v[66:69], v134, s[14:15] offset:1024
	s_waitcnt lgkmcnt(1)
	v_mfma_f32_32x32x16_f16 v[34:49], v[164:167], v[160:163], v[34:49]
	ds_read_b128 v[160:163], v144 offset:32
	s_waitcnt vmcnt(8)
	ds_write_b128 v142, v[98:101] offset:18432
	s_waitcnt lgkmcnt(2)
	v_mfma_f32_32x32x16_f16 v[18:33], v[156:159], v[168:171], v[18:33]
	ds_read_b128 v[156:159], v145 offset:36896
	global_load_dwordx4 v[70:73], v138, s[16:17] offset:1024
	v_mfma_f32_32x32x16_f16 v[2:17], v[164:167], v[168:171], v[2:17]
	ds_read_b128 v[164:167], v145 offset:41504
	ds_read_b128 v[168:171], v144 offset:4640
	s_waitcnt vmcnt(8)
	ds_write_b128 v142, v[102:105] offset:55296
	s_waitcnt lgkmcnt(3)
	v_mfma_f32_32x32x16_f16 v[50:65], v[156:159], v[160:163], v[50:65]
	global_load_dwordx4 v[74:77], v135, s[14:15] offset:1024
	s_waitcnt lgkmcnt(2)
	v_mfma_f32_32x32x16_f16 v[34:49], v[164:167], v[160:163], v[34:49]
	ds_read_b128 v[160:163], v144 offset:64
	s_waitcnt vmcnt(8)
	ds_write_b128 v142, v[106:109] offset:23040
	s_waitcnt lgkmcnt(3)
	v_mfma_f32_32x32x16_f16 v[18:33], v[156:159], v[168:171], v[18:33]
	ds_read_b128 v[156:159], v145 offset:36928
	global_load_dwordx4 v[78:81], v139, s[16:17] offset:1024
	v_mfma_f32_32x32x16_f16 v[2:17], v[164:167], v[168:171], v[2:17]
	ds_read_b128 v[164:167], v145 offset:41536
	ds_read_b128 v[168:171], v144 offset:4672
	s_waitcnt vmcnt(8)
	ds_write_b128 v142, v[110:113] offset:59904
	s_waitcnt lgkmcnt(3)
	v_mfma_f32_32x32x16_f16 v[50:65], v[156:159], v[160:163], v[50:65]
	global_load_dwordx4 v[82:85], v136, s[14:15] offset:1024
	s_waitcnt lgkmcnt(2)
	v_mfma_f32_32x32x16_f16 v[34:49], v[164:167], v[160:163], v[34:49]
	ds_read_b128 v[160:163], v144 offset:96
	s_waitcnt vmcnt(8)
	ds_write_b128 v142, v[114:117] offset:27648
	s_waitcnt lgkmcnt(3)
	v_mfma_f32_32x32x16_f16 v[18:33], v[156:159], v[168:171], v[18:33]
	ds_read_b128 v[156:159], v145 offset:36960
	global_load_dwordx4 v[86:89], v140, s[16:17] offset:1024
	v_mfma_f32_32x32x16_f16 v[2:17], v[164:167], v[168:171], v[2:17]
	ds_read_b128 v[164:167], v145 offset:41568
	ds_read_b128 v[168:171], v144 offset:4704
	s_waitcnt vmcnt(8)
	ds_write_b128 v142, v[118:121] offset:64512
	s_waitcnt lgkmcnt(3)
	v_mfma_f32_32x32x16_f16 v[50:65], v[156:159], v[160:163], v[50:65]
	global_load_dwordx4 v[90:93], v137, s[14:15] offset:1024
	s_waitcnt lgkmcnt(2)
	v_mfma_f32_32x32x16_f16 v[34:49], v[164:167], v[160:163], v[34:49]
	s_waitcnt vmcnt(8)
	ds_write_b128 v142, v[122:125] offset:32256
	s_waitcnt lgkmcnt(2)
	v_mfma_f32_32x32x16_f16 v[18:33], v[156:159], v[168:171], v[18:33]
	global_load_dwordx4 v[94:97], v141, s[16:17] offset:1024
	v_mfma_f32_32x32x16_f16 v[2:17], v[164:167], v[168:171], v[2:17]
	s_waitcnt vmcnt(8)
	ds_write_b128 v143, v[126:129] offset:64512
	s_setprio 0
	s_waitcnt lgkmcnt(0)
	s_barrier
; #define GEMM_GLOAD(P, kt_) { GEMM_GL1(P, 0, kt_) GEMM_GL1(P, 1, kt_) GEMM_GL1(P, 2, kt_) GEMM_GL1(P, 3, kt_) }
; #define GEMM_LSTORE(P, buf_) { GEMM_LS1(P, 0, buf_) GEMM_LS1(P, 1, buf_) GEMM_LS1(P, 2, buf_) GEMM_LS1(P, 3, buf_) }
; template <bool DEEP>
; DI void gemm_mainloop_t(const u16* __restrict__ Ag, int lda, const u16* __restrict__ Bg, int ldb, int K, char* ldsraw,
;                         f32x16 (&acc)[2][2], int akstep) {
;     ...
;     for (int kt = 0; kt < nk; kt += 2) {
;       if (kt + 2 < nk) GEMM_GLOAD(x, kt + 2);
;       GEMM_COMPUTE(0);
;       GEMM_LSTORE(y, 1);
;       __syncthreads();
;       if (kt + 3 < nk) GEMM_GLOAD(y, kt + 3);
;       GEMM_COMPUTE(1);
;       if (kt + 2 < nk) GEMM_LSTORE(x, 0);
;       __syncthreads();
	s_setprio 1
	ds_read_b128 v[156:159], v145 offset:55296
	ds_read_b128 v[160:163], v144 offset:18432
	ds_read_b128 v[164:167], v145 offset:59904
	ds_read_b128 v[168:171], v144 offset:23040
	s_waitcnt lgkmcnt(2)
	v_mfma_f32_32x32x16_f16 v[50:65], v[156:159], v[160:163], v[50:65]
	global_load_dwordx4 v[98:101], v134, s[14:15] offset:1152
	s_waitcnt lgkmcnt(1)
	v_mfma_f32_32x32x16_f16 v[34:49], v[164:167], v[160:163], v[34:49]
	ds_read_b128 v[160:163], v144 offset:18464
	s_waitcnt vmcnt(8)
	ds_write_b128 v142, v[66:69]
	s_waitcnt lgkmcnt(2)
	v_mfma_f32_32x32x16_f16 v[18:33], v[156:159], v[168:171], v[18:33]
	ds_read_b128 v[156:159], v145 offset:55328
	global_load_dwordx4 v[102:105], v138, s[16:17] offset:1152
	v_mfma_f32_32x32x16_f16 v[2:17], v[164:167], v[168:171], v[2:17]
	ds_read_b128 v[164:167], v145 offset:59936
	ds_read_b128 v[168:171], v144 offset:23072
	s_waitcnt vmcnt(8)
	ds_write_b128 v142, v[70:73] offset:36864
	s_waitcnt lgkmcnt(3)
	v_mfma_f32_32x32x16_f16 v[50:65], v[156:159], v[160:163], v[50:65]
	global_load_dwordx4 v[106:109], v135, s[14:15] offset:1152
	s_waitcnt lgkmcnt(2)
	v_mfma_f32_32x32x16_f16 v[34:49], v[164:167], v[160:163], v[34:49]
	ds_read_b128 v[160:163], v144 offset:18496
	s_waitcnt vmcnt(8)
	ds_write_b128 v142, v[74:77] offset:4608
	s_waitcnt lgkmcnt(3)
	v_mfma_f32_32x32x16_f16 v[18:33], v[156:159], v[168:171], v[18:33]
	ds_read_b128 v[156:159], v145 offset:55360
	global_load_dwordx4 v[110:113], v139, s[16:17] offset:1152
	v_mfma_f32_32x32x16_f16 v[2:17], v[164:167], v[168:171], v[2:17]
	ds_read_b128 v[164:167], v145 offset:59968
	ds_read_b128 v[168:171], v144 offset:23104
	s_waitcnt vmcnt(8)
	ds_write_b128 v142, v[78:81] offset:41472
	s_waitcnt lgkmcnt(3)
	v_mfma_f32_32x32x16_f16 v[50:65], v[156:159], v[160:163], v[50:65]
	global_load_dwordx4 v[114:117], v136, s[14:15] offset:1152
	s_waitcnt lgkmcnt(2)
	v_mfma_f32_32x32x16_f16 v[34:49], v[164:167], v[160:163], v[34:49]
	ds_read_b128 v[160:163], v144 offset:18528
	s_waitcnt vmcnt(8)
	ds_write_b128 v142, v[82:85] offset:9216
	s_waitcnt lgkmcnt(3)
	v_mfma_f32_32x32x16_f16 v[18:33], v[156:159], v[168:171], v[18:33]
	ds_read_b128 v[156:159], v145 offset:55392
	global_load_dwordx4 v[118:121], v140, s[16:17] offset:1152
	v_mfma_f32_32x32x16_f16 v[2:17], v[164:167], v[168:171], v[2:17]
	ds_read_b128 v[164:167], v145 offset:60000
	ds_read_b128 v[168:171], v144 offset:23136
	s_waitcnt vmcnt(8)
	ds_write_b128 v142, v[86:89] offset:46080
	s_waitcnt lgkmcnt(3)
	v_mfma_f32_32x32x16_f16 v[50:65], v[156:159], v[160:163], v[50:65]
	global_load_dwordx4 v[122:125], v137, s[14:15] offset:1152
	s_waitcnt lgkmcnt(2)
	v_mfma_f32_32x32x16_f16 v[34:49], v[164:167], v[160:163], v[34:49]
	s_waitcnt vmcnt(8)
	ds_write_b128 v142, v[90:93] offset:13824
	s_waitcnt lgkmcnt(2)
	v_mfma_f32_32x32x16_f16 v[18:33], v[156:159], v[168:171], v[18:33]
	global_load_dwordx4 v[126:129], v141, s[16:17] offset:1152
	v_mfma_f32_32x32x16_f16 v[2:17], v[164:167], v[168:171], v[2:17]
	s_waitcnt vmcnt(8)
	ds_write_b128 v142, v[94:97] offset:50688
	s_setprio 0
	s_waitcnt lgkmcnt(0)
	s_barrier
	s_setprio 1
	ds_read_b128 v[156:159], v145 offset:36864
	ds_read_b128 v[160:163], v144
	ds_read_b128 v[164:167], v145 offset:41472
	ds_read_b128 v[168:171], v144 offset:4608
	s_waitcnt lgkmcnt(2)
	v_mfma_f32_32x32x16_f16 v[50:65], v[156:159], v[160:163], v[50:65]
	global_load_dwordx4 v[66:69], v134, s[14:15] offset:1280
	s_waitcnt lgkmcnt(1)
	v_mfma_f32_32x32x16_f16 v[34:49], v[164:167], v[160:163], v[34:49]
	ds_read_b128 v[160:163], v144 offset:32
	s_waitcnt vmcnt(8)
	ds_write_b128 v142, v[98:101] offset:18432
	s_waitcnt lgkmcnt(2)
	v_mfma_f32_32x32x16_f16 v[18:33], v[156:159], v[168:171], v[18:33]
	ds_read_b128 v[156:159], v145 offset:36896
	global_load_dwordx4 v[70:73], v138, s[16:17] offset:1280
	v_mfma_f32_32x32x16_f16 v[2:17], v[164:167], v[168:171], v[2:17]
	ds_read_b128 v[164:167], v145 offset:41504
	ds_read_b128 v[168:171], v144 offset:4640
	s_waitcnt vmcnt(8)
	ds_write_b128 v142, v[102:105] offset:55296
	s_waitcnt lgkmcnt(3)
	v_mfma_f32_32x32x16_f16 v[50:65], v[156:159], v[160:163], v[50:65]
	global_load_dwordx4 v[74:77], v135, s[14:15] offset:1280
	s_waitcnt lgkmcnt(2)
	v_mfma_f32_32x32x16_f16 v[34:49], v[164:167], v[160:163], v[34:49]
	ds_read_b128 v[160:163], v144 offset:64
	s_waitcnt vmcnt(8)
	ds_write_b128 v142, v[106:109] offset:23040
	s_waitcnt lgkmcnt(3)
	v_mfma_f32_32x32x16_f16 v[18:33], v[156:159], v[168:171], v[18:33]
	ds_read_b128 v[156:159], v145 offset:36928
	global_load_dwordx4 v[78:81], v139, s[16:17] offset:1280
	v_mfma_f32_32x32x16_f16 v[2:17], v[164:167], v[168:171], v[2:17]
	ds_read_b128 v[164:167], v145 offset:41536
	ds_read_b128 v[168:171], v144 offset:4672
	s_waitcnt vmcnt(8)
	ds_write_b128 v142, v[110:113] offset:59904
	s_waitcnt lgkmcnt(3)
	v_mfma_f32_32x32x16_f16 v[50:65], v[156:159], v[160:163], v[50:65]
	global_load_dwordx4 v[82:85], v136, s[14:15] offset:1280
	s_waitcnt lgkmcnt(2)
	v_mfma_f32_32x32x16_f16 v[34:49], v[164:167], v[160:163], v[34:49]
	ds_read_b128 v[160:163], v144 offset:96
	s_waitcnt vmcnt(8)
	ds_write_b128 v142, v[114:117] offset:27648
	s_waitcnt lgkmcnt(3)
	v_mfma_f32_32x32x16_f16 v[18:33], v[156:159], v[168:171], v[18:33]
	ds_read_b128 v[156:159], v145 offset:36960
	global_load_dwordx4 v[86:89], v140, s[16:17] offset:1280
	v_mfma_f32_32x32x16_f16 v[2:17], v[164:167], v[168:171], v[2:17]
	ds_read_b128 v[164:167], v145 offset:41568
	ds_read_b128 v[168:171], v144 offset:4704
	s_waitcnt vmcnt(8)
	ds_write_b128 v142, v[118:121] offset:64512
	s_waitcnt lgkmcnt(3)
	v_mfma_f32_32x32x16_f16 v[50:65], v[156:159], v[160:163], v[50:65]
	global_load_dwordx4 v[90:93], v137, s[14:15] offset:1280
	s_waitcnt lgkmcnt(2)
	v_mfma_f32_32x32x16_f16 v[34:49], v[164:167], v[160:163], v[34:49]
	s_waitcnt vmcnt(8)
	ds_write_b128 v142, v[122:125] offset:32256
	s_waitcnt lgkmcnt(2)
	v_mfma_f32_32x32x16_f16 v[18:33], v[156:159], v[168:171], v[18:33]
	global_load_dwordx4 v[94:97], v141, s[16:17] offset:1280
	v_mfma_f32_32x32x16_f16 v[2:17], v[164:167], v[168:171], v[2:17]
	s_waitcnt vmcnt(8)
	ds_write_b128 v143, v[126:129] offset:64512
	s_setprio 0
	s_waitcnt lgkmcnt(0)
	s_barrier
; #define GEMM_GLOAD(P, kt_) { GEMM_GL1(P, 0, kt_) GEMM_GL1(P, 1, kt_) GEMM_GL1(P, 2, kt_) GEMM_GL1(P, 3, kt_) }
; #define GEMM_LSTORE(P, buf_) { GEMM_LS1(P, 0, buf_) GEMM_LS1(P, 1, buf_) GEMM_LS1(P, 2, buf_) GEMM_LS1(P, 3, buf_) }
; template <bool DEEP>
; DI void gemm_mainloop_t(const u16* __restrict__ Ag, int lda, const u16* __restrict__ Bg, int ldb, int K, char* ldsraw,
;                         f32x16 (&acc)[2][2], int akstep) {
;     ...
;     for (int kt = 0; kt < nk; kt += 2) {
;       if (kt + 2 < nk) GEMM_GLOAD(x, kt + 2);
;       GEMM_COMPUTE(0);
;       GEMM_LSTORE(y, 1);
;       __syncthreads();
;       if (kt + 3 < nk) GEMM_GLOAD(y, kt + 3);
;       GEMM_COMPUTE(1);
;       if (kt + 2 < nk) GEMM_LSTORE(x, 0);
;       __syncthreads();
	s_setprio 1
	ds_read_b128 v[156:159], v145 offset:55296
	ds_read_b128 v[160:163], v144 offset:18432
	ds_read_b128 v[164:167], v145 offset:59904
	ds_read_b128 v[168:171], v144 offset:23040
	s_waitcnt lgkmcnt(2)
	v_mfma_f32_32x32x16_f16 v[50:65], v[156:159], v[160:163], v[50:65]
	global_load_dwordx4 v[98:101], v134, s[14:15] offset:1408
	s_waitcnt lgkmcnt(1)
	v_mfma_f32_32x32x16_f16 v[34:49], v[164:167], v[160:163], v[34:49]
	ds_read_b128 v[160:163], v144 offset:18464
	s_waitcnt vmcnt(8)
	ds_write_b128 v142, v[66:69]
	s_waitcnt lgkmcnt(2)
	v_mfma_f32_32x32x16_f16 v[18:33], v[156:159], v[168:171], v[18:33]
	ds_read_b128 v[156:159], v145 offset:55328
	global_load_dwordx4 v[102:105], v138, s[16:17] offset:1408
	v_mfma_f32_32x32x16_f16 v[2:17], v[164:167], v[168:171], v[2:17]
	ds_read_b128 v[164:167], v145 offset:59936
	ds_read_b128 v[168:171], v144 offset:23072
	s_waitcnt vmcnt(8)
	ds_write_b128 v142, v[70:73] offset:36864
	s_waitcnt lgkmcnt(3)
	v_mfma_f32_32x32x16_f16 v[50:65], v[156:159], v[160:163], v[50:65]
	global_load_dwordx4 v[106:109], v135, s[14:15] offset:1408
	s_waitcnt lgkmcnt(2)
	v_mfma_f32_32x32x16_f16 v[34:49], v[164:167], v[160:163], v[34:49]
	ds_read_b128 v[160:163], v144 offset:18496
	s_waitcnt vmcnt(8)
	ds_write_b128 v142, v[74:77] offset:4608
	s_waitcnt lgkmcnt(3)
	v_mfma_f32_32x32x16_f16 v[18:33], v[156:159], v[168:171], v[18:33]
	ds_read_b128 v[156:159], v145 offset:55360
	global_load_dwordx4 v[110:113], v139, s[16:17] offset:1408
	v_mfma_f32_32x32x16_f16 v[2:17], v[164:167], v[168:171], v[2:17]
	ds_read_b128 v[164:167], v145 offset:59968
	ds_read_b128 v[168:171], v144 offset:23104
	s_waitcnt vmcnt(8)
	ds_write_b128 v142, v[78:81] offset:41472
	s_waitcnt lgkmcnt(3)
	v_mfma_f32_32x32x16_f16 v[50:65], v[156:159], v[160:163], v[50:65]
	global_load_dwordx4 v[114:117], v136, s[14:15] offset:1408
	s_waitcnt lgkmcnt(2)
	v_mfma_f32_32x32x16_f16 v[34:49], v[164:167], v[160:163], v[34:49]
	ds_read_b128 v[160:163], v144 offset:18528
	s_waitcnt vmcnt(8)
	ds_write_b128 v142, v[82:85] offset:9216
	s_waitcnt lgkmcnt(3)
	v_mfma_f32_32x32x16_f16 v[18:33], v[156:159], v[168:171], v[18:33]
	ds_read_b128 v[156:159], v145 offset:55392
	global_load_dwordx4 v[118:121], v140, s[16:17] offset:1408
	v_mfma_f32_32x32x16_f16 v[2:17], v[164:167], v[168:171], v[2:17]
	ds_read_b128 v[164:167], v145 offset:60000
	ds_read_b128 v[168:171], v144 offset:23136
	s_waitcnt vmcnt(8)
	ds_write_b128 v142, v[86:89] offset:46080
	s_waitcnt lgkmcnt(3)
	v_mfma_f32_32x32x16_f16 v[50:65], v[156:159], v[160:163], v[50:65]
	global_load_dwordx4 v[122:125], v137, s[14:15] offset:1408
	s_waitcnt lgkmcnt(2)
	v_mfma_f32_32x32x16_f16 v[34:49], v[164:167], v[160:163], v[34:49]
	s_waitcnt vmcnt(8)
	ds_write_b128 v142, v[90:93] offset:13824
	s_waitcnt lgkmcnt(2)
	v_mfma_f32_32x32x16_f16 v[18:33], v[156:159], v[168:171], v[18:33]
	global_load_dwordx4 v[126:129], v141, s[16:17] offset:1408
	v_mfma_f32_32x32x16_f16 v[2:17], v[164:167], v[168:171], v[2:17]
	s_waitcnt vmcnt(8)
	ds_write_b128 v142, v[94:97] offset:50688
	s_setprio 0
	s_waitcnt lgkmcnt(0)
	s_barrier
	s_setprio 1
	ds_read_b128 v[156:159], v145 offset:36864
	ds_read_b128 v[160:163], v144
	ds_read_b128 v[164:167], v145 offset:41472
	ds_read_b128 v[168:171], v144 offset:4608
	s_waitcnt lgkmcnt(2)
	v_mfma_f32_32x32x16_f16 v[50:65], v[156:159], v[160:163], v[50:65]
	global_load_dwordx4 v[66:69], v134, s[14:15] offset:1536
	s_waitcnt lgkmcnt(1)
	v_mfma_f32_32x32x16_f16 v[34:49], v[164:167], v[160:163], v[34:49]
	ds_read_b128 v[160:163], v144 offset:32
	s_waitcnt vmcnt(8)
	ds_write_b128 v142, v[98:101] offset:18432
	s_waitcnt lgkmcnt(2)
	v_mfma_f32_32x32x16_f16 v[18:33], v[156:159], v[168:171], v[18:33]
	ds_read_b128 v[156:159], v145 offset:36896
	global_load_dwordx4 v[70:73], v138, s[16:17] offset:1536
	v_mfma_f32_32x32x16_f16 v[2:17], v[164:167], v[168:171], v[2:17]
	ds_read_b128 v[164:167], v145 offset:41504
	ds_read_b128 v[168:171], v144 offset:4640
	s_waitcnt vmcnt(8)
	ds_write_b128 v142, v[102:105] offset:55296
	s_waitcnt lgkmcnt(3)
	v_mfma_f32_32x32x16_f16 v[50:65], v[156:159], v[160:163], v[50:65]
	global_load_dwordx4 v[74:77], v135, s[14:15] offset:1536
	s_waitcnt lgkmcnt(2)
	v_mfma_f32_32x32x16_f16 v[34:49], v[164:167], v[160:163], v[34:49]
	ds_read_b128 v[160:163], v144 offset:64
	s_waitcnt vmcnt(8)
	ds_write_b128 v142, v[106:109] offset:23040
	s_waitcnt lgkmcnt(3)
	v_mfma_f32_32x32x16_f16 v[18:33], v[156:159], v[168:171], v[18:33]
	ds_read_b128 v[156:159], v145 offset:36928
	global_load_dwordx4 v[78:81], v139, s[16:17] offset:1536
	v_mfma_f32_32x32x16_f16 v[2:17], v[164:167], v[168:171], v[2:17]
	ds_read_b128 v[164:167], v145 offset:41536
	ds_read_b128 v[168:171], v144 offset:4672
	s_waitcnt vmcnt(8)
	ds_write_b128 v142, v[110:113] offset:59904
	s_waitcnt lgkmcnt(3)
	v_mfma_f32_32x32x16_f16 v[50:65], v[156:159], v[160:163], v[50:65]
	global_load_dwordx4 v[82:85], v136, s[14:15] offset:1536
	s_waitcnt lgkmcnt(2)
	v_mfma_f32_32x32x16_f16 v[34:49], v[164:167], v[160:163], v[34:49]
	ds_read_b128 v[160:163], v144 offset:96
	s_waitcnt vmcnt(8)
	ds_write_b128 v142, v[114:117] offset:27648
	s_waitcnt lgkmcnt(3)
	v_mfma_f32_32x32x16_f16 v[18:33], v[156:159], v[168:171], v[18:33]
	ds_read_b128 v[156:159], v145 offset:36960
	global_load_dwordx4 v[86:89], v140, s[16:17] offset:1536
	v_mfma_f32_32x32x16_f16 v[2:17], v[164:167], v[168:171], v[2:17]
	ds_read_b128 v[164:167], v145 offset:41568
	ds_read_b128 v[168:171], v144 offset:4704
	s_waitcnt vmcnt(8)
	ds_write_b128 v142, v[118:121] offset:64512
	s_waitcnt lgkmcnt(3)
	v_mfma_f32_32x32x16_f16 v[50:65], v[156:159], v[160:163], v[50:65]
	global_load_dwordx4 v[90:93], v137, s[14:15] offset:1536
	s_waitcnt lgkmcnt(2)
	v_mfma_f32_32x32x16_f16 v[34:49], v[164:167], v[160:163], v[34:49]
	s_waitcnt vmcnt(8)
	ds_write_b128 v142, v[122:125] offset:32256
	s_waitcnt lgkmcnt(2)
	v_mfma_f32_32x32x16_f16 v[18:33], v[156:159], v[168:171], v[18:33]
	global_load_dwordx4 v[94:97], v141, s[16:17] offset:1536
	v_mfma_f32_32x32x16_f16 v[2:17], v[164:167], v[168:171], v[2:17]
	s_waitcnt vmcnt(8)
	ds_write_b128 v143, v[126:129] offset:64512
	s_setprio 0
	s_waitcnt lgkmcnt(0)
	s_barrier
; #define GEMM_GLOAD(P, kt_) { GEMM_GL1(P, 0, kt_) GEMM_GL1(P, 1, kt_) GEMM_GL1(P, 2, kt_) GEMM_GL1(P, 3, kt_) }
; #define GEMM_LSTORE(P, buf_) { GEMM_LS1(P, 0, buf_) GEMM_LS1(P, 1, buf_) GEMM_LS1(P, 2, buf_) GEMM_LS1(P, 3, buf_) }
; template <bool DEEP>
; DI void gemm_mainloop_t(const u16* __restrict__ Ag, int lda, const u16* __restrict__ Bg, int ldb, int K, char* ldsraw,
;                         f32x16 (&acc)[2][2], int akstep) {
;     ...
;     for (int kt = 0; kt < nk; kt += 2) {
;       if (kt + 2 < nk) GEMM_GLOAD(x, kt + 2);
;       GEMM_COMPUTE(0);
;       GEMM_LSTORE(y, 1);
;       __syncthreads();
;       if (kt + 3 < nk) GEMM_GLOAD(y, kt + 3);
;       GEMM_COMPUTE(1);
;       if (kt + 2 < nk) GEMM_LSTORE(x, 0);
;       __syncthreads();
	s_setprio 1
	ds_read_b128 v[156:159], v145 offset:55296
	ds_read_b128 v[160:163], v144 offset:18432
	ds_read_b128 v[164:167], v145 offset:59904
	ds_read_b128 v[168:171], v144 offset:23040
	s_waitcnt lgkmcnt(2)
	v_mfma_f32_32x32x16_f16 v[50:65], v[156:159], v[160:163], v[50:65]
	global_load_dwordx4 v[98:101], v134, s[14:15] offset:1664
	s_waitcnt lgkmcnt(1)
	v_mfma_f32_32x32x16_f16 v[34:49], v[164:167], v[160:163], v[34:49]
	ds_read_b128 v[160:163], v144 offset:18464
	s_waitcnt vmcnt(8)
	ds_write_b128 v142, v[66:69]
	s_waitcnt lgkmcnt(2)
	v_mfma_f32_32x32x16_f16 v[18:33], v[156:159], v[168:171], v[18:33]
	ds_read_b128 v[156:159], v145 offset:55328
	global_load_dwordx4 v[102:105], v138, s[16:17] offset:1664
	v_mfma_f32_32x32x16_f16 v[2:17], v[164:167], v[168:171], v[2:17]
	ds_read_b128 v[164:167], v145 offset:59936
	ds_read_b128 v[168:171], v144 offset:23072
	s_waitcnt vmcnt(8)
	ds_write_b128 v142, v[70:73] offset:36864
	s_waitcnt lgkmcnt(3)
	v_mfma_f32_32x32x16_f16 v[50:65], v[156:159], v[160:163], v[50:65]
	global_load_dwordx4 v[106:109], v135, s[14:15] offset:1664
	s_waitcnt lgkmcnt(2)
	v_mfma_f32_32x32x16_f16 v[34:49], v[164:167], v[160:163], v[34:49]
	ds_read_b128 v[160:163], v144 offset:18496
	s_waitcnt vmcnt(8)
	ds_write_b128 v142, v[74:77] offset:4608
	s_waitcnt lgkmcnt(3)
	v_mfma_f32_32x32x16_f16 v[18:33], v[156:159], v[168:171], v[18:33]
	ds_read_b128 v[156:159], v145 offset:55360
	global_load_dwordx4 v[110:113], v139, s[16:17] offset:1664
	v_mfma_f32_32x32x16_f16 v[2:17], v[164:167], v[168:171], v[2:17]
	ds_read_b128 v[164:167], v145 offset:59968
	ds_read_b128 v[168:171], v144 offset:23104
	s_waitcnt vmcnt(8)
	ds_write_b128 v142, v[78:81] offset:41472
	s_waitcnt lgkmcnt(3)
	v_mfma_f32_32x32x16_f16 v[50:65], v[156:159], v[160:163], v[50:65]
	global_load_dwordx4 v[114:117], v136, s[14:15] offset:1664
	s_waitcnt lgkmcnt(2)
	v_mfma_f32_32x32x16_f16 v[34:49], v[164:167], v[160:163], v[34:49]
	ds_read_b128 v[160:163], v144 offset:18528
	s_waitcnt vmcnt(8)
	ds_write_b128 v142, v[82:85] offset:9216
	s_waitcnt lgkmcnt(3)
	v_mfma_f32_32x32x16_f16 v[18:33], v[156:159], v[168:171], v[18:33]
	ds_read_b128 v[156:159], v145 offset:55392
	global_load_dwordx4 v[118:121], v140, s[16:17] offset:1664
	v_mfma_f32_32x32x16_f16 v[2:17], v[164:167], v[168:171], v[2:17]
	ds_read_b128 v[164:167], v145 offset:60000
	ds_read_b128 v[168:171], v144 offset:23136
	s_waitcnt vmcnt(8)
	ds_write_b128 v142, v[86:89] offset:46080
	s_waitcnt lgkmcnt(3)
	v_mfma_f32_32x32x16_f16 v[50:65], v[156:159], v[160:163], v[50:65]
	global_load_dwordx4 v[122:125], v137, s[14:15] offset:1664
	s_waitcnt lgkmcnt(2)
	v_mfma_f32_32x32x16_f16 v[34:49], v[164:167], v[160:163], v[34:49]
	s_waitcnt vmcnt(8)
	ds_write_b128 v142, v[90:93] offset:13824
	s_waitcnt lgkmcnt(2)
	v_mfma_f32_32x32x16_f16 v[18:33], v[156:159], v[168:171], v[18:33]
	global_load_dwordx4 v[126:129], v141, s[16:17] offset:1664
	v_mfma_f32_32x32x16_f16 v[2:17], v[164:167], v[168:171], v[2:17]
	s_waitcnt vmcnt(8)
	ds_write_b128 v142, v[94:97] offset:50688
	s_setprio 0
	s_waitcnt lgkmcnt(0)
	s_barrier
	s_setprio 1
	ds_read_b128 v[156:159], v145 offset:36864
	ds_read_b128 v[160:163], v144
	ds_read_b128 v[164:167], v145 offset:41472
	ds_read_b128 v[168:171], v144 offset:4608
	s_waitcnt lgkmcnt(2)
	v_mfma_f32_32x32x16_f16 v[50:65], v[156:159], v[160:163], v[50:65]
	global_load_dwordx4 v[66:69], v134, s[14:15] offset:1792
	s_waitcnt lgkmcnt(1)
	v_mfma_f32_32x32x16_f16 v[34:49], v[164:167], v[160:163], v[34:49]
	ds_read_b128 v[160:163], v144 offset:32
	s_waitcnt vmcnt(8)
	ds_write_b128 v142, v[98:101] offset:18432
	s_waitcnt lgkmcnt(2)
	v_mfma_f32_32x32x16_f16 v[18:33], v[156:159], v[168:171], v[18:33]
	ds_read_b128 v[156:159], v145 offset:36896
	global_load_dwordx4 v[70:73], v138, s[16:17] offset:1792
	v_mfma_f32_32x32x16_f16 v[2:17], v[164:167], v[168:171], v[2:17]
	ds_read_b128 v[164:167], v145 offset:41504
	ds_read_b128 v[168:171], v144 offset:4640
	s_waitcnt vmcnt(8)
	ds_write_b128 v142, v[102:105] offset:55296
	s_waitcnt lgkmcnt(3)
	v_mfma_f32_32x32x16_f16 v[50:65], v[156:159], v[160:163], v[50:65]
	global_load_dwordx4 v[74:77], v135, s[14:15] offset:1792
	s_waitcnt lgkmcnt(2)
	v_mfma_f32_32x32x16_f16 v[34:49], v[164:167], v[160:163], v[34:49]
	ds_read_b128 v[160:163], v144 offset:64
	s_waitcnt vmcnt(8)
	ds_write_b128 v142, v[106:109] offset:23040
	s_waitcnt lgkmcnt(3)
	v_mfma_f32_32x32x16_f16 v[18:33], v[156:159], v[168:171], v[18:33]
	ds_read_b128 v[156:159], v145 offset:36928
	global_load_dwordx4 v[78:81], v139, s[16:17] offset:1792
	v_mfma_f32_32x32x16_f16 v[2:17], v[164:167], v[168:171], v[2:17]
	ds_read_b128 v[164:167], v145 offset:41536
	ds_read_b128 v[168:171], v144 offset:4672
	s_waitcnt vmcnt(8)
	ds_write_b128 v142, v[110:113] offset:59904
	s_waitcnt lgkmcnt(3)
	v_mfma_f32_32x32x16_f16 v[50:65], v[156:159], v[160:163], v[50:65]
	global_load_dwordx4 v[82:85], v136, s[14:15] offset:1792
	s_waitcnt lgkmcnt(2)
	v_mfma_f32_32x32x16_f16 v[34:49], v[164:167], v[160:163], v[34:49]
	ds_read_b128 v[160:163], v144 offset:96
	s_waitcnt vmcnt(8)
	ds_write_b128 v142, v[114:117] offset:27648
	s_waitcnt lgkmcnt(3)
	v_mfma_f32_32x32x16_f16 v[18:33], v[156:159], v[168:171], v[18:33]
	ds_read_b128 v[156:159], v145 offset:36960
	global_load_dwordx4 v[86:89], v140, s[16:17] offset:1792
	v_mfma_f32_32x32x16_f16 v[2:17], v[164:167], v[168:171], v[2:17]
	ds_read_b128 v[164:167], v145 offset:41568
	ds_read_b128 v[168:171], v144 offset:4704
	s_waitcnt vmcnt(8)
	ds_write_b128 v142, v[118:121] offset:64512
	s_waitcnt lgkmcnt(3)
	v_mfma_f32_32x32x16_f16 v[50:65], v[156:159], v[160:163], v[50:65]
	global_load_dwordx4 v[90:93], v137, s[14:15] offset:1792
	s_waitcnt lgkmcnt(2)
	v_mfma_f32_32x32x16_f16 v[34:49], v[164:167], v[160:163], v[34:49]
	s_waitcnt vmcnt(8)
	ds_write_b128 v142, v[122:125] offset:32256
	s_waitcnt lgkmcnt(2)
	v_mfma_f32_32x32x16_f16 v[18:33], v[156:159], v[168:171], v[18:33]
	global_load_dwordx4 v[94:97], v141, s[16:17] offset:1792
	v_mfma_f32_32x32x16_f16 v[2:17], v[164:167], v[168:171], v[2:17]
	s_waitcnt vmcnt(8)
	ds_write_b128 v143, v[126:129] offset:64512
	s_setprio 0
	s_waitcnt lgkmcnt(0)
	s_barrier
; #define GEMM_GLOAD(P, kt_) { GEMM_GL1(P, 0, kt_) GEMM_GL1(P, 1, kt_) GEMM_GL1(P, 2, kt_) GEMM_GL1(P, 3, kt_) }
; #define GEMM_LSTORE(P, buf_) { GEMM_LS1(P, 0, buf_) GEMM_LS1(P, 1, buf_) GEMM_LS1(P, 2, buf_) GEMM_LS1(P, 3, buf_) }
; template <bool DEEP>
; DI void gemm_mainloop_t(const u16* __restrict__ Ag, int lda, const u16* __restrict__ Bg, int ldb, int K, char* ldsraw,
;                         f32x16 (&acc)[2][2], int akstep) {
;     ...
;     for (int kt = 0; kt < nk; kt += 2) {
;       if (kt + 2 < nk) GEMM_GLOAD(x, kt + 2);
;       GEMM_COMPUTE(0);
;       GEMM_LSTORE(y, 1);
;       __syncthreads();
;       if (kt + 3 < nk) GEMM_GLOAD(y, kt + 3);
;       GEMM_COMPUTE(1);
;       if (kt + 2 < nk) GEMM_LSTORE(x, 0);
;       __syncthreads();
	s_setprio 1
	ds_read_b128 v[156:159], v145 offset:55296
	ds_read_b128 v[160:163], v144 offset:18432
	ds_read_b128 v[164:167], v145 offset:59904
	ds_read_b128 v[168:171], v144 offset:23040
	s_waitcnt lgkmcnt(2)
	v_mfma_f32_32x32x16_f16 v[50:65], v[156:159], v[160:163], v[50:65]
	global_load_dwordx4 v[98:101], v134, s[14:15] offset:1920
	s_waitcnt lgkmcnt(1)
	v_mfma_f32_32x32x16_f16 v[34:49], v[164:167], v[160:163], v[34:49]
	ds_read_b128 v[160:163], v144 offset:18464
	s_waitcnt vmcnt(8)
	ds_write_b128 v142, v[66:69]
	s_waitcnt lgkmcnt(2)
	v_mfma_f32_32x32x16_f16 v[18:33], v[156:159], v[168:171], v[18:33]
	ds_read_b128 v[156:159], v145 offset:55328
	global_load_dwordx4 v[102:105], v138, s[16:17] offset:1920
	v_mfma_f32_32x32x16_f16 v[2:17], v[164:167], v[168:171], v[2:17]
	ds_read_b128 v[164:167], v145 offset:59936
	ds_read_b128 v[168:171], v144 offset:23072
	s_waitcnt vmcnt(8)
	ds_write_b128 v142, v[70:73] offset:36864
	s_waitcnt lgkmcnt(3)
	v_mfma_f32_32x32x16_f16 v[50:65], v[156:159], v[160:163], v[50:65]
	global_load_dwordx4 v[106:109], v135, s[14:15] offset:1920
	s_waitcnt lgkmcnt(2)
	v_mfma_f32_32x32x16_f16 v[34:49], v[164:167], v[160:163], v[34:49]
	ds_read_b128 v[160:163], v144 offset:18496
	s_waitcnt vmcnt(8)
	ds_write_b128 v142, v[74:77] offset:4608
	s_waitcnt lgkmcnt(3)
	v_mfma_f32_32x32x16_f16 v[18:33], v[156:159], v[168:171], v[18:33]
	ds_read_b128 v[156:159], v145 offset:55360
	global_load_dwordx4 v[110:113], v139, s[16:17] offset:1920
	v_mfma_f32_32x32x16_f16 v[2:17], v[164:167], v[168:171], v[2:17]
	ds_read_b128 v[164:167], v145 offset:59968
	ds_read_b128 v[168:171], v144 offset:23104
	s_waitcnt vmcnt(8)
	ds_write_b128 v142, v[78:81] offset:41472
	s_waitcnt lgkmcnt(3)
	v_mfma_f32_32x32x16_f16 v[50:65], v[156:159], v[160:163], v[50:65]
	global_load_dwordx4 v[114:117], v136, s[14:15] offset:1920
	s_waitcnt lgkmcnt(2)
	v_mfma_f32_32x32x16_f16 v[34:49], v[164:167], v[160:163], v[34:49]
	ds_read_b128 v[160:163], v144 offset:18528
	s_waitcnt vmcnt(8)
	ds_write_b128 v142, v[82:85] offset:9216
	s_waitcnt lgkmcnt(3)
	v_mfma_f32_32x32x16_f16 v[18:33], v[156:159], v[168:171], v[18:33]
	ds_read_b128 v[156:159], v145 offset:55392
	global_load_dwordx4 v[118:121], v140, s[16:17] offset:1920
	v_mfma_f32_32x32x16_f16 v[2:17], v[164:167], v[168:171], v[2:17]
	ds_read_b128 v[164:167], v145 offset:60000
	ds_read_b128 v[168:171], v144 offset:23136
	s_waitcnt vmcnt(8)
	ds_write_b128 v142, v[86:89] offset:46080
	s_waitcnt lgkmcnt(3)
	v_mfma_f32_32x32x16_f16 v[50:65], v[156:159], v[160:163], v[50:65]
	global_load_dwordx4 v[122:125], v137, s[14:15] offset:1920
	s_waitcnt lgkmcnt(2)
	v_mfma_f32_32x32x16_f16 v[34:49], v[164:167], v[160:163], v[34:49]
	s_waitcnt vmcnt(8)
	ds_write_b128 v142, v[90:93] offset:13824
	s_waitcnt lgkmcnt(2)
	v_mfma_f32_32x32x16_f16 v[18:33], v[156:159], v[168:171], v[18:33]
	global_load_dwordx4 v[126:129], v141, s[16:17] offset:1920
	v_mfma_f32_32x32x16_f16 v[2:17], v[164:167], v[168:171], v[2:17]
	s_waitcnt vmcnt(8)
	ds_write_b128 v142, v[94:97] offset:50688
	s_setprio 0
	s_waitcnt lgkmcnt(0)
	s_barrier
; #define GEMM_LSTORE(P, buf_) { GEMM_LS1(P, 0, buf_) GEMM_LS1(P, 1, buf_) GEMM_LS1(P, 2, buf_) GEMM_LS1(P, 3, buf_) }
; template <bool DEEP>
; DI void gemm_mainloop_t(const u16* __restrict__ Ag, int lda, const u16* __restrict__ Bg, int ldb, int K, char* ldsraw,
;                         f32x16 (&acc)[2][2], int akstep) {
;     ...
;       GEMM_COMPUTE(1);
;       if (kt + 2 < nk) GEMM_LSTORE(x, 0);
;       __syncthreads();
; DI void phase1(const Params& p, int l, char* lds) {
;     ...
;     {
;       const int col0 = nt * 128 + wn * 64;
;       const float* gain = nullptr;
;       float sc = 1.f;
;       if (col0 < 512) { gain = p.qn_a + l * 64; sc = QSCALE; }
;       else if (col0 < 1024) { gain = p.kn_a + l * 64; }
;       else if (col0 >= QC && col0 < QC + 512) { gain = p.qn_c + l * 64; sc = QSCALE; }
;       else if ((col0 >= KSC && col0 < KSC + 128) || (col0 >= KWC && col0 < KWC + 128)) { gain = p.kn_c + l * 64; }
	s_setprio 1
	ds_read_b128 v[156:159], v145 offset:36864
	ds_read_b128 v[160:163], v144
	ds_read_b128 v[164:167], v145 offset:41472
	ds_read_b128 v[168:171], v144 offset:4608
	s_waitcnt lgkmcnt(2)
	v_mfma_f32_32x32x16_f16 v[50:65], v[156:159], v[160:163], v[50:65]
	s_waitcnt lgkmcnt(1)
	v_mfma_f32_32x32x16_f16 v[34:49], v[164:167], v[160:163], v[34:49]
	ds_read_b128 v[160:163], v144 offset:32
	s_waitcnt vmcnt(7)
	ds_write_b128 v142, v[98:101] offset:18432
	s_waitcnt lgkmcnt(2)
	v_mfma_f32_32x32x16_f16 v[18:33], v[156:159], v[168:171], v[18:33]
	ds_read_b128 v[156:159], v145 offset:36896
	v_mfma_f32_32x32x16_f16 v[2:17], v[164:167], v[168:171], v[2:17]
	ds_read_b128 v[164:167], v145 offset:41504
	ds_read_b128 v[168:171], v144 offset:4640
	s_waitcnt vmcnt(6)
	ds_write_b128 v142, v[102:105] offset:55296
	s_waitcnt lgkmcnt(3)
	v_mfma_f32_32x32x16_f16 v[50:65], v[156:159], v[160:163], v[50:65]
	s_waitcnt lgkmcnt(2)
	v_mfma_f32_32x32x16_f16 v[34:49], v[164:167], v[160:163], v[34:49]
	ds_read_b128 v[160:163], v144 offset:64
	s_waitcnt vmcnt(5)
	ds_write_b128 v142, v[106:109] offset:23040
	s_waitcnt lgkmcnt(3)
	v_mfma_f32_32x32x16_f16 v[18:33], v[156:159], v[168:171], v[18:33]
	ds_read_b128 v[156:159], v145 offset:36928
	v_mfma_f32_32x32x16_f16 v[2:17], v[164:167], v[168:171], v[2:17]
	ds_read_b128 v[164:167], v145 offset:41536
	ds_read_b128 v[168:171], v144 offset:4672
	s_waitcnt vmcnt(4)
	ds_write_b128 v142, v[110:113] offset:59904
	s_waitcnt lgkmcnt(3)
	v_mfma_f32_32x32x16_f16 v[50:65], v[156:159], v[160:163], v[50:65]
	s_waitcnt lgkmcnt(2)
	v_mfma_f32_32x32x16_f16 v[34:49], v[164:167], v[160:163], v[34:49]
	ds_read_b128 v[160:163], v144 offset:96
	s_waitcnt vmcnt(3)
	ds_write_b128 v142, v[114:117] offset:27648
	s_waitcnt lgkmcnt(3)
	v_mfma_f32_32x32x16_f16 v[18:33], v[156:159], v[168:171], v[18:33]
	ds_read_b128 v[156:159], v145 offset:36960
	v_mfma_f32_32x32x16_f16 v[2:17], v[164:167], v[168:171], v[2:17]
	ds_read_b128 v[164:167], v145 offset:41568
	ds_read_b128 v[168:171], v144 offset:4704
	s_waitcnt vmcnt(2)
	ds_write_b128 v142, v[118:121] offset:64512
	s_waitcnt lgkmcnt(3)
	v_mfma_f32_32x32x16_f16 v[50:65], v[156:159], v[160:163], v[50:65]
	s_waitcnt lgkmcnt(2)
	v_mfma_f32_32x32x16_f16 v[34:49], v[164:167], v[160:163], v[34:49]
	s_waitcnt vmcnt(1)
	ds_write_b128 v142, v[122:125] offset:32256
	s_waitcnt lgkmcnt(2)
	v_mfma_f32_32x32x16_f16 v[18:33], v[156:159], v[168:171], v[18:33]
	v_mfma_f32_32x32x16_f16 v[2:17], v[164:167], v[168:171], v[2:17]
	s_waitcnt vmcnt(0)
	ds_write_b128 v143, v[126:129] offset:64512
	s_setprio 0
	s_waitcnt lgkmcnt(0)
	s_barrier
	s_setprio 1
	ds_read_b128 v[156:159], v145 offset:55296
	ds_read_b128 v[160:163], v144 offset:18432
	ds_read_b128 v[164:167], v145 offset:59904
	ds_read_b128 v[168:171], v144 offset:23040
	s_waitcnt lgkmcnt(2)
	v_mfma_f32_32x32x16_f16 v[50:65], v[156:159], v[160:163], v[50:65]
	s_waitcnt lgkmcnt(1)
	v_mfma_f32_32x32x16_f16 v[34:49], v[164:167], v[160:163], v[34:49]
	ds_read_b128 v[160:163], v144 offset:18464
	s_waitcnt lgkmcnt(1)
	v_mfma_f32_32x32x16_f16 v[18:33], v[156:159], v[168:171], v[18:33]
	ds_read_b128 v[156:159], v145 offset:55328
	v_mfma_f32_32x32x16_f16 v[2:17], v[164:167], v[168:171], v[2:17]
	ds_read_b128 v[164:167], v145 offset:59936
	ds_read_b128 v[168:171], v144 offset:23072
	s_waitcnt lgkmcnt(2)
	v_mfma_f32_32x32x16_f16 v[50:65], v[156:159], v[160:163], v[50:65]
	s_waitcnt lgkmcnt(1)
	v_mfma_f32_32x32x16_f16 v[34:49], v[164:167], v[160:163], v[34:49]
	ds_read_b128 v[160:163], v144 offset:18496
	s_waitcnt lgkmcnt(1)
	v_mfma_f32_32x32x16_f16 v[18:33], v[156:159], v[168:171], v[18:33]
	ds_read_b128 v[156:159], v145 offset:55360
	v_mfma_f32_32x32x16_f16 v[2:17], v[164:167], v[168:171], v[2:17]
	ds_read_b128 v[164:167], v145 offset:59968
	ds_read_b128 v[168:171], v144 offset:23104
	s_waitcnt lgkmcnt(2)
	v_mfma_f32_32x32x16_f16 v[50:65], v[156:159], v[160:163], v[50:65]
	s_waitcnt lgkmcnt(1)
	v_mfma_f32_32x32x16_f16 v[34:49], v[164:167], v[160:163], v[34:49]
	ds_read_b128 v[160:163], v144 offset:18528
	s_waitcnt lgkmcnt(1)
	v_mfma_f32_32x32x16_f16 v[18:33], v[156:159], v[168:171], v[18:33]
	ds_read_b128 v[156:159], v145 offset:55392
	v_mfma_f32_32x32x16_f16 v[2:17], v[164:167], v[168:171], v[2:17]
	ds_read_b128 v[164:167], v145 offset:60000
	ds_read_b128 v[168:171], v144 offset:23136
	s_waitcnt lgkmcnt(2)
	v_mfma_f32_32x32x16_f16 v[50:65], v[156:159], v[160:163], v[50:65]
	s_waitcnt lgkmcnt(1)
	v_mfma_f32_32x32x16_f16 v[34:49], v[164:167], v[160:163], v[34:49]
	s_waitcnt lgkmcnt(0)
	v_mfma_f32_32x32x16_f16 v[18:33], v[156:159], v[168:171], v[18:33]
	v_mfma_f32_32x32x16_f16 v[2:17], v[164:167], v[168:171], v[2:17]
	s_setprio 0
	s_nop 1
	s_lshl_b32 s16, s0, 7
	v_or_b32_e32 v83, s16, v131
	s_movk_i32 s1, 0x1ff
	v_cmp_lt_i32_e32 vcc, s1, v83
	v_mov_b32_e32 v68, 0x3e38aa3b
	v_mov_b64_e32 v[66:67], s[10:11]
	s_barrier
	s_and_saveexec_b64 s[14:15], vcc
	s_cbranch_execz .LBB0_230
	s_mov_b32 s1, 1.0
	s_cmpk_lt_u32 s16, 0x400
	s_mov_b64 s[16:17], s[8:9]
	s_cbranch_scc1 .LBB0_229
	s_and_b32 s16, s18, 0x3fffff80
	s_mov_b32 s1, 0x3e38aa3b
	s_cmpk_eq_i32 s16, 0x300
	s_mov_b64 s[16:17], s[6:7]
	s_cbranch_scc1 .LBB0_229
	s_cmp_lt_i32 s0, 32
	s_cbranch_scc1 .LBB0_224
	s_cmp_eq_u32 s0, 32
	s_cselect_b64 s[16:17], -1, 0
	s_cbranch_execz .LBB0_225
	s_branch .LBB0_226

; DI int TID() { int t = threadIdx.x; asm volatile("" : "+v"(t)); return t; }
; #define GEMM_GLOAD(P, kt_) { GEMM_GL1(P, 0, kt_) GEMM_GL1(P, 1, kt_) GEMM_GL1(P, 2, kt_) GEMM_GL1(P, 3, kt_) }
; #define GEMM_LSTORE(P, buf_) { GEMM_LS1(P, 0, buf_) GEMM_LS1(P, 1, buf_) GEMM_LS1(P, 2, buf_) GEMM_LS1(P, 3, buf_) }
; template <bool DEEP>
; DI void gemm_mainloop_t(const u16* __restrict__ Ag, int lda, const u16* __restrict__ Bg, int ldb, int K, char* ldsraw,
;                         f32x16 (&acc)[2][2], int akstep) {
;   const int tid = TID(), lane = tid & 63, w = tid >> 6, wm = w >> 1, wn = w & 1, r = lane & 31, h = lane >> 5;
;   u16* As = (u16*)ldsraw;
;   u16* Bs = As + 2 * 128 * LDT;
;   uint4 xa0, xa1, xa2, xa3, xb0, xb1, xb2, xb3;
;   const int nk = K >> 6;
;   const int row0 = tid >> 3, cc = tid & 7;
;   if (DEEP) {
;     uint4 ya0, ya1, ya2, ya3, yb0, yb1, yb2, yb3;
;     GEMM_GLOAD(x, 0);
;     GEMM_GLOAD(y, 1);
;     GEMM_LSTORE(x, 0);
;     __syncthreads();
;     for (int kt = 0; kt < nk; kt += 2) {
;       if (kt + 2 < nk) GEMM_GLOAD(x, kt + 2);
;       GEMM_COMPUTE(0);
;       GEMM_LSTORE(y, 1);
;       __syncthreads();
;       if (kt + 3 < nk) GEMM_GLOAD(y, kt + 3);
;       GEMM_COMPUTE(1);
;       if (kt + 2 < nk) GEMM_LSTORE(x, 0);
;       __syncthreads();
; DI void phase5(const Params& p, int l, const float* xin, float* xout, char* lds) {
;     ...
;   for (int tile = blockIdx.x; tile < 128 * 8; tile += gridDim.x) {
;     const int nt = tile & 7, mt = tile >> 3;
;     f32x16 acc[2][2];
;     zero_acc(acc);
;     gemm_mainloop(p.z + (size_t)mt * 128 * ZS, ZS, WOT(l) + (size_t)nt * 128 * 1024, 1024, 1024, lds, acc);
.LBB0_1116:
	s_ashr_i32 s0, s4, 3
	s_and_b32 s5, s4, 7
	s_ashr_i32 s1, s0, 31
	s_mul_i32 s6, s0, 0x198000
	s_waitcnt vmcnt(31)
	s_mul_hi_i32 s7, s0, 0x198000
	s_add_u32 s6, s14, s6
	s_addc_u32 s7, s15, s7
	s_lshl_b32 s8, s5, 18
	s_add_u32 s8, s2, s8
	s_addc_u32 s9, s3, 0
	v_lshrrev_b32_e32 v148, 3, v209
	v_and_b32_e32 v149, 7, v209
	v_lshlrev_b32_e32 v149, 4, v149
	v_mov_b32_e32 v150, v148
	v_mul_u32_u24_e32 v136, 0x3300, v150
	v_add_u32_e32 v136, v136, v149
	v_mul_u32_u24_e32 v140, 0x800, v150
	v_add_u32_e32 v140, v140, v149
	v_add_u32_e32 v150, 32, v148
	v_mul_u32_u24_e32 v137, 0x3300, v150
	v_add_u32_e32 v137, v137, v149
	v_mul_u32_u24_e32 v141, 0x800, v150
	v_add_u32_e32 v141, v141, v149
	v_add_u32_e32 v150, 64, v148
	v_mul_u32_u24_e32 v138, 0x3300, v150
	v_add_u32_e32 v138, v138, v149
	v_mul_u32_u24_e32 v142, 0x800, v150
	v_add_u32_e32 v142, v142, v149
	v_add_u32_e32 v150, 96, v148
	v_mul_u32_u24_e32 v139, 0x3300, v150
	v_add_u32_e32 v139, v139, v149
	v_mul_u32_u24_e32 v143, 0x800, v150
	v_add_u32_e32 v143, v143, v149
	v_mul_u32_u24_e32 v144, 0x90, v148
	v_add_u32_e32 v144, v144, v149
	v_add_u32_e32 v145, 0x1200, v144
	v_and_b32_e32 v148, 31, v209
	v_bfe_u32 v149, v209, 5, 1
	v_lshlrev_b32_e32 v149, 4, v149
	v_bfe_u32 v150, v209, 7, 1
	v_lshl_add_u32 v150, v150, 6, v148
	v_mul_u32_u24_e32 v146, 0x90, v150
	v_add_u32_e32 v146, v146, v149
	v_bfe_u32 v150, v209, 6, 1
	v_lshl_add_u32 v150, v150, 6, v148
	v_mul_u32_u24_e32 v147, 0x90, v150
	v_add_u32_e32 v147, v147, v149
	global_load_dwordx4 v[66:69], v136, s[6:7]
	global_load_dwordx4 v[70:73], v140, s[8:9]
	global_load_dwordx4 v[74:77], v137, s[6:7]
	global_load_dwordx4 v[78:81], v141, s[8:9]
	global_load_dwordx4 v[82:85], v138, s[6:7]
	global_load_dwordx4 v[86:89], v142, s[8:9]
	global_load_dwordx4 v[90:93], v139, s[6:7]
	global_load_dwordx4 v[94:97], v143, s[8:9]
	global_load_dwordx4 v[98:101], v136, s[6:7] offset:128
	global_load_dwordx4 v[102:105], v140, s[8:9] offset:128
	global_load_dwordx4 v[106:109], v137, s[6:7] offset:128
	global_load_dwordx4 v[110:113], v141, s[8:9] offset:128
	global_load_dwordx4 v[114:117], v138, s[6:7] offset:128
	global_load_dwordx4 v[118:121], v142, s[8:9] offset:128
	global_load_dwordx4 v[122:125], v139, s[6:7] offset:128
	global_load_dwordx4 v[126:129], v143, s[8:9] offset:128
	s_waitcnt vmcnt(15)
	ds_write_b128 v144, v[66:69]
	s_waitcnt vmcnt(14)
	ds_write_b128 v144, v[70:73] offset:36864
	s_waitcnt vmcnt(13)
	ds_write_b128 v144, v[74:77] offset:4608
	s_waitcnt vmcnt(12)
	ds_write_b128 v144, v[78:81] offset:41472
	s_waitcnt vmcnt(11)
	ds_write_b128 v144, v[82:85] offset:9216
	s_waitcnt vmcnt(10)
	ds_write_b128 v144, v[86:89] offset:46080
	s_waitcnt vmcnt(9)
	ds_write_b128 v144, v[90:93] offset:13824
	s_waitcnt vmcnt(8)
	ds_write_b128 v144, v[94:97] offset:50688
	s_waitcnt lgkmcnt(0)
	s_barrier
	s_setprio 1
	ds_read_b128 v[154:157], v147 offset:36864
	ds_read_b128 v[158:161], v146
	ds_read_b128 v[162:165], v147 offset:41472
	ds_read_b128 v[166:169], v146 offset:4608
	s_waitcnt lgkmcnt(2)
	v_mfma_f32_32x32x16_f16 v[50:65], v[154:157], v[158:161], 0
	global_load_dwordx4 v[66:69], v136, s[6:7] offset:256
	s_waitcnt lgkmcnt(1)
	v_mfma_f32_32x32x16_f16 v[34:49], v[162:165], v[158:161], 0
	ds_read_b128 v[158:161], v146 offset:32
	s_waitcnt vmcnt(8)
	ds_write_b128 v144, v[98:101] offset:18432
	s_waitcnt lgkmcnt(2)
	v_mfma_f32_32x32x16_f16 v[18:33], v[154:157], v[166:169], 0
	ds_read_b128 v[154:157], v147 offset:36896
	global_load_dwordx4 v[70:73], v140, s[8:9] offset:256
	v_mfma_f32_32x32x16_f16 v[2:17], v[162:165], v[166:169], 0
	ds_read_b128 v[162:165], v147 offset:41504
	ds_read_b128 v[166:169], v146 offset:4640
	s_waitcnt vmcnt(8)
	ds_write_b128 v144, v[102:105] offset:55296
	s_waitcnt lgkmcnt(3)
	v_mfma_f32_32x32x16_f16 v[50:65], v[154:157], v[158:161], v[50:65]
	global_load_dwordx4 v[74:77], v137, s[6:7] offset:256
	s_waitcnt lgkmcnt(2)
	v_mfma_f32_32x32x16_f16 v[34:49], v[162:165], v[158:161], v[34:49]
	ds_read_b128 v[158:161], v146 offset:64
	s_waitcnt vmcnt(8)
	ds_write_b128 v144, v[106:109] offset:23040
	s_waitcnt lgkmcnt(3)
	v_mfma_f32_32x32x16_f16 v[18:33], v[154:157], v[166:169], v[18:33]
	ds_read_b128 v[154:157], v147 offset:36928
	global_load_dwordx4 v[78:81], v141, s[8:9] offset:256
	v_mfma_f32_32x32x16_f16 v[2:17], v[162:165], v[166:169], v[2:17]
	ds_read_b128 v[162:165], v147 offset:41536
	ds_read_b128 v[166:169], v146 offset:4672
	s_waitcnt vmcnt(8)
	ds_write_b128 v144, v[110:113] offset:59904
	s_waitcnt lgkmcnt(3)
	v_mfma_f32_32x32x16_f16 v[50:65], v[154:157], v[158:161], v[50:65]
	global_load_dwordx4 v[82:85], v138, s[6:7] offset:256
	s_waitcnt lgkmcnt(2)
	v_mfma_f32_32x32x16_f16 v[34:49], v[162:165], v[158:161], v[34:49]
	ds_read_b128 v[158:161], v146 offset:96
	s_waitcnt vmcnt(8)
	ds_write_b128 v144, v[114:117] offset:27648
	s_waitcnt lgkmcnt(3)
	v_mfma_f32_32x32x16_f16 v[18:33], v[154:157], v[166:169], v[18:33]
	ds_read_b128 v[154:157], v147 offset:36960
	global_load_dwordx4 v[86:89], v142, s[8:9] offset:256
	v_mfma_f32_32x32x16_f16 v[2:17], v[162:165], v[166:169], v[2:17]
	ds_read_b128 v[162:165], v147 offset:41568
	ds_read_b128 v[166:169], v146 offset:4704
	s_waitcnt vmcnt(8)
	ds_write_b128 v144, v[118:121] offset:64512
	s_waitcnt lgkmcnt(3)
	v_mfma_f32_32x32x16_f16 v[50:65], v[154:157], v[158:161], v[50:65]
	global_load_dwordx4 v[90:93], v139, s[6:7] offset:256
	s_waitcnt lgkmcnt(2)
	v_mfma_f32_32x32x16_f16 v[34:49], v[162:165], v[158:161], v[34:49]
	s_waitcnt vmcnt(8)
	ds_write_b128 v144, v[122:125] offset:32256
	s_waitcnt lgkmcnt(2)
	v_mfma_f32_32x32x16_f16 v[18:33], v[154:157], v[166:169], v[18:33]
	global_load_dwordx4 v[94:97], v143, s[8:9] offset:256
	v_mfma_f32_32x32x16_f16 v[2:17], v[162:165], v[166:169], v[2:17]
	s_waitcnt vmcnt(8)
	ds_write_b128 v145, v[126:129] offset:64512
	s_setprio 0
	s_waitcnt lgkmcnt(0)
	s_barrier
; #define GEMM_GLOAD(P, kt_) { GEMM_GL1(P, 0, kt_) GEMM_GL1(P, 1, kt_) GEMM_GL1(P, 2, kt_) GEMM_GL1(P, 3, kt_) }
; #define GEMM_LSTORE(P, buf_) { GEMM_LS1(P, 0, buf_) GEMM_LS1(P, 1, buf_) GEMM_LS1(P, 2, buf_) GEMM_LS1(P, 3, buf_) }
; template <bool DEEP>
; DI void gemm_mainloop_t(const u16* __restrict__ Ag, int lda, const u16* __restrict__ Bg, int ldb, int K, char* ldsraw,
;                         f32x16 (&acc)[2][2], int akstep) {
;     ...
;     for (int kt = 0; kt < nk; kt += 2) {
;       if (kt + 2 < nk) GEMM_GLOAD(x, kt + 2);
;       GEMM_COMPUTE(0);
;       GEMM_LSTORE(y, 1);
;       __syncthreads();
;       if (kt + 3 < nk) GEMM_GLOAD(y, kt + 3);
;       GEMM_COMPUTE(1);
;       if (kt + 2 < nk) GEMM_LSTORE(x, 0);
;       __syncthreads();
	s_setprio 1
	ds_read_b128 v[154:157], v147 offset:55296
	ds_read_b128 v[158:161], v146 offset:18432
	ds_read_b128 v[162:165], v147 offset:59904
	ds_read_b128 v[166:169], v146 offset:23040
	s_waitcnt lgkmcnt(2)
	v_mfma_f32_32x32x16_f16 v[50:65], v[154:157], v[158:161], v[50:65]
	global_load_dwordx4 v[98:101], v136, s[6:7] offset:384
	s_waitcnt lgkmcnt(1)
	v_mfma_f32_32x32x16_f16 v[34:49], v[162:165], v[158:161], v[34:49]
	ds_read_b128 v[158:161], v146 offset:18464
	s_waitcnt vmcnt(8)
	ds_write_b128 v144, v[66:69]
	s_waitcnt lgkmcnt(2)
	v_mfma_f32_32x32x16_f16 v[18:33], v[154:157], v[166:169], v[18:33]
	ds_read_b128 v[154:157], v147 offset:55328
	global_load_dwordx4 v[102:105], v140, s[8:9] offset:384
	v_mfma_f32_32x32x16_f16 v[2:17], v[162:165], v[166:169], v[2:17]
	ds_read_b128 v[162:165], v147 offset:59936
	ds_read_b128 v[166:169], v146 offset:23072
	s_waitcnt vmcnt(8)
	ds_write_b128 v144, v[70:73] offset:36864
	s_waitcnt lgkmcnt(3)
	v_mfma_f32_32x32x16_f16 v[50:65], v[154:157], v[158:161], v[50:65]
	global_load_dwordx4 v[106:109], v137, s[6:7] offset:384
	s_waitcnt lgkmcnt(2)
	v_mfma_f32_32x32x16_f16 v[34:49], v[162:165], v[158:161], v[34:49]
	ds_read_b128 v[158:161], v146 offset:18496
	s_waitcnt vmcnt(8)
	ds_write_b128 v144, v[74:77] offset:4608
	s_waitcnt lgkmcnt(3)
	v_mfma_f32_32x32x16_f16 v[18:33], v[154:157], v[166:169], v[18:33]
	ds_read_b128 v[154:157], v147 offset:55360
	global_load_dwordx4 v[110:113], v141, s[8:9] offset:384
	v_mfma_f32_32x32x16_f16 v[2:17], v[162:165], v[166:169], v[2:17]
	ds_read_b128 v[162:165], v147 offset:59968
	ds_read_b128 v[166:169], v146 offset:23104
	s_waitcnt vmcnt(8)
	ds_write_b128 v144, v[78:81] offset:41472
	s_waitcnt lgkmcnt(3)
	v_mfma_f32_32x32x16_f16 v[50:65], v[154:157], v[158:161], v[50:65]
	global_load_dwordx4 v[114:117], v138, s[6:7] offset:384
	s_waitcnt lgkmcnt(2)
	v_mfma_f32_32x32x16_f16 v[34:49], v[162:165], v[158:161], v[34:49]
	ds_read_b128 v[158:161], v146 offset:18528
	s_waitcnt vmcnt(8)
	ds_write_b128 v144, v[82:85] offset:9216
	s_waitcnt lgkmcnt(3)
	v_mfma_f32_32x32x16_f16 v[18:33], v[154:157], v[166:169], v[18:33]
	ds_read_b128 v[154:157], v147 offset:55392
	global_load_dwordx4 v[118:121], v142, s[8:9] offset:384
	v_mfma_f32_32x32x16_f16 v[2:17], v[162:165], v[166:169], v[2:17]
	ds_read_b128 v[162:165], v147 offset:60000
	ds_read_b128 v[166:169], v146 offset:23136
	s_waitcnt vmcnt(8)
	ds_write_b128 v144, v[86:89] offset:46080
	s_waitcnt lgkmcnt(3)
	v_mfma_f32_32x32x16_f16 v[50:65], v[154:157], v[158:161], v[50:65]
	global_load_dwordx4 v[122:125], v139, s[6:7] offset:384
	s_waitcnt lgkmcnt(2)
	v_mfma_f32_32x32x16_f16 v[34:49], v[162:165], v[158:161], v[34:49]
	s_waitcnt vmcnt(8)
	ds_write_b128 v144, v[90:93] offset:13824
	s_waitcnt lgkmcnt(2)
	v_mfma_f32_32x32x16_f16 v[18:33], v[154:157], v[166:169], v[18:33]
	global_load_dwordx4 v[126:129], v143, s[8:9] offset:384
	v_mfma_f32_32x32x16_f16 v[2:17], v[162:165], v[166:169], v[2:17]
	s_waitcnt vmcnt(8)
	ds_write_b128 v144, v[94:97] offset:50688
	s_setprio 0
	s_waitcnt lgkmcnt(0)
	s_barrier
	s_setprio 1
	ds_read_b128 v[154:157], v147 offset:36864
	ds_read_b128 v[158:161], v146
	ds_read_b128 v[162:165], v147 offset:41472
	ds_read_b128 v[166:169], v146 offset:4608
	s_waitcnt lgkmcnt(2)
	v_mfma_f32_32x32x16_f16 v[50:65], v[154:157], v[158:161], v[50:65]
	global_load_dwordx4 v[66:69], v136, s[6:7] offset:512
	s_waitcnt lgkmcnt(1)
	v_mfma_f32_32x32x16_f16 v[34:49], v[162:165], v[158:161], v[34:49]
	ds_read_b128 v[158:161], v146 offset:32
	s_waitcnt vmcnt(8)
	ds_write_b128 v144, v[98:101] offset:18432
	s_waitcnt lgkmcnt(2)
	v_mfma_f32_32x32x16_f16 v[18:33], v[154:157], v[166:169], v[18:33]
	ds_read_b128 v[154:157], v147 offset:36896
	global_load_dwordx4 v[70:73], v140, s[8:9] offset:512
	v_mfma_f32_32x32x16_f16 v[2:17], v[162:165], v[166:169], v[2:17]
	ds_read_b128 v[162:165], v147 offset:41504
	ds_read_b128 v[166:169], v146 offset:4640
	s_waitcnt vmcnt(8)
	ds_write_b128 v144, v[102:105] offset:55296
	s_waitcnt lgkmcnt(3)
	v_mfma_f32_32x32x16_f16 v[50:65], v[154:157], v[158:161], v[50:65]
	global_load_dwordx4 v[74:77], v137, s[6:7] offset:512
	s_waitcnt lgkmcnt(2)
	v_mfma_f32_32x32x16_f16 v[34:49], v[162:165], v[158:161], v[34:49]
	ds_read_b128 v[158:161], v146 offset:64
	s_waitcnt vmcnt(8)
	ds_write_b128 v144, v[106:109] offset:23040
	s_waitcnt lgkmcnt(3)
	v_mfma_f32_32x32x16_f16 v[18:33], v[154:157], v[166:169], v[18:33]
	ds_read_b128 v[154:157], v147 offset:36928
	global_load_dwordx4 v[78:81], v141, s[8:9] offset:512
	v_mfma_f32_32x32x16_f16 v[2:17], v[162:165], v[166:169], v[2:17]
	ds_read_b128 v[162:165], v147 offset:41536
	ds_read_b128 v[166:169], v146 offset:4672
	s_waitcnt vmcnt(8)
	ds_write_b128 v144, v[110:113] offset:59904
	s_waitcnt lgkmcnt(3)
	v_mfma_f32_32x32x16_f16 v[50:65], v[154:157], v[158:161], v[50:65]
	global_load_dwordx4 v[82:85], v138, s[6:7] offset:512
	s_waitcnt lgkmcnt(2)
	v_mfma_f32_32x32x16_f16 v[34:49], v[162:165], v[158:161], v[34:49]
	ds_read_b128 v[158:161], v146 offset:96
	s_waitcnt vmcnt(8)
	ds_write_b128 v144, v[114:117] offset:27648
	s_waitcnt lgkmcnt(3)
	v_mfma_f32_32x32x16_f16 v[18:33], v[154:157], v[166:169], v[18:33]
	ds_read_b128 v[154:157], v147 offset:36960
	global_load_dwordx4 v[86:89], v142, s[8:9] offset:512
	v_mfma_f32_32x32x16_f16 v[2:17], v[162:165], v[166:169], v[2:17]
	ds_read_b128 v[162:165], v147 offset:41568
	ds_read_b128 v[166:169], v146 offset:4704
	s_waitcnt vmcnt(8)
	ds_write_b128 v144, v[118:121] offset:64512
	s_waitcnt lgkmcnt(3)
	v_mfma_f32_32x32x16_f16 v[50:65], v[154:157], v[158:161], v[50:65]
	global_load_dwordx4 v[90:93], v139, s[6:7] offset:512
	s_waitcnt lgkmcnt(2)
	v_mfma_f32_32x32x16_f16 v[34:49], v[162:165], v[158:161], v[34:49]
	s_waitcnt vmcnt(8)
	ds_write_b128 v144, v[122:125] offset:32256
	s_waitcnt lgkmcnt(2)
	v_mfma_f32_32x32x16_f16 v[18:33], v[154:157], v[166:169], v[18:33]
	global_load_dwordx4 v[94:97], v143, s[8:9] offset:512
	v_mfma_f32_32x32x16_f16 v[2:17], v[162:165], v[166:169], v[2:17]
	s_waitcnt vmcnt(8)
	ds_write_b128 v145, v[126:129] offset:64512
	s_setprio 0
	s_waitcnt lgkmcnt(0)
	s_barrier
; #define GEMM_GLOAD(P, kt_) { GEMM_GL1(P, 0, kt_) GEMM_GL1(P, 1, kt_) GEMM_GL1(P, 2, kt_) GEMM_GL1(P, 3, kt_) }
; #define GEMM_LSTORE(P, buf_) { GEMM_LS1(P, 0, buf_) GEMM_LS1(P, 1, buf_) GEMM_LS1(P, 2, buf_) GEMM_LS1(P, 3, buf_) }
; template <bool DEEP>
; DI void gemm_mainloop_t(const u16* __restrict__ Ag, int lda, const u16* __restrict__ Bg, int ldb, int K, char* ldsraw,
;                         f32x16 (&acc)[2][2], int akstep) {
;     ...
;     for (int kt = 0; kt < nk; kt += 2) {
;       if (kt + 2 < nk) GEMM_GLOAD(x, kt + 2);
;       GEMM_COMPUTE(0);
;       GEMM_LSTORE(y, 1);
;       __syncthreads();
;       if (kt + 3 < nk) GEMM_GLOAD(y, kt + 3);
;       GEMM_COMPUTE(1);
;       if (kt + 2 < nk) GEMM_LSTORE(x, 0);
;       __syncthreads();
	s_setprio 1
	ds_read_b128 v[154:157], v147 offset:55296
	ds_read_b128 v[158:161], v146 offset:18432
	ds_read_b128 v[162:165], v147 offset:59904
	ds_read_b128 v[166:169], v146 offset:23040
	s_waitcnt lgkmcnt(2)
	v_mfma_f32_32x32x16_f16 v[50:65], v[154:157], v[158:161], v[50:65]
	global_load_dwordx4 v[98:101], v136, s[6:7] offset:640
	s_waitcnt lgkmcnt(1)
	v_mfma_f32_32x32x16_f16 v[34:49], v[162:165], v[158:161], v[34:49]
	ds_read_b128 v[158:161], v146 offset:18464
	s_waitcnt vmcnt(8)
	ds_write_b128 v144, v[66:69]
	s_waitcnt lgkmcnt(2)
	v_mfma_f32_32x32x16_f16 v[18:33], v[154:157], v[166:169], v[18:33]
	ds_read_b128 v[154:157], v147 offset:55328
	global_load_dwordx4 v[102:105], v140, s[8:9] offset:640
	v_mfma_f32_32x32x16_f16 v[2:17], v[162:165], v[166:169], v[2:17]
	ds_read_b128 v[162:165], v147 offset:59936
	ds_read_b128 v[166:169], v146 offset:23072
	s_waitcnt vmcnt(8)
	ds_write_b128 v144, v[70:73] offset:36864
	s_waitcnt lgkmcnt(3)
	v_mfma_f32_32x32x16_f16 v[50:65], v[154:157], v[158:161], v[50:65]
	global_load_dwordx4 v[106:109], v137, s[6:7] offset:640
	s_waitcnt lgkmcnt(2)
	v_mfma_f32_32x32x16_f16 v[34:49], v[162:165], v[158:161], v[34:49]
	ds_read_b128 v[158:161], v146 offset:18496
	s_waitcnt vmcnt(8)
	ds_write_b128 v144, v[74:77] offset:4608
	s_waitcnt lgkmcnt(3)
	v_mfma_f32_32x32x16_f16 v[18:33], v[154:157], v[166:169], v[18:33]
	ds_read_b128 v[154:157], v147 offset:55360
	global_load_dwordx4 v[110:113], v141, s[8:9] offset:640
	v_mfma_f32_32x32x16_f16 v[2:17], v[162:165], v[166:169], v[2:17]
	ds_read_b128 v[162:165], v147 offset:59968
	ds_read_b128 v[166:169], v146 offset:23104
	s_waitcnt vmcnt(8)
	ds_write_b128 v144, v[78:81] offset:41472
	s_waitcnt lgkmcnt(3)
	v_mfma_f32_32x32x16_f16 v[50:65], v[154:157], v[158:161], v[50:65]
	global_load_dwordx4 v[114:117], v138, s[6:7] offset:640
	s_waitcnt lgkmcnt(2)
	v_mfma_f32_32x32x16_f16 v[34:49], v[162:165], v[158:161], v[34:49]
	ds_read_b128 v[158:161], v146 offset:18528
	s_waitcnt vmcnt(8)
	ds_write_b128 v144, v[82:85] offset:9216
	s_waitcnt lgkmcnt(3)
	v_mfma_f32_32x32x16_f16 v[18:33], v[154:157], v[166:169], v[18:33]
	ds_read_b128 v[154:157], v147 offset:55392
	global_load_dwordx4 v[118:121], v142, s[8:9] offset:640
	v_mfma_f32_32x32x16_f16 v[2:17], v[162:165], v[166:169], v[2:17]
	ds_read_b128 v[162:165], v147 offset:60000
	ds_read_b128 v[166:169], v146 offset:23136
	s_waitcnt vmcnt(8)
	ds_write_b128 v144, v[86:89] offset:46080
	s_waitcnt lgkmcnt(3)
	v_mfma_f32_32x32x16_f16 v[50:65], v[154:157], v[158:161], v[50:65]
	global_load_dwordx4 v[122:125], v139, s[6:7] offset:640
	s_waitcnt lgkmcnt(2)
	v_mfma_f32_32x32x16_f16 v[34:49], v[162:165], v[158:161], v[34:49]
	s_waitcnt vmcnt(8)
	ds_write_b128 v144, v[90:93] offset:13824
	s_waitcnt lgkmcnt(2)
	v_mfma_f32_32x32x16_f16 v[18:33], v[154:157], v[166:169], v[18:33]
	global_load_dwordx4 v[126:129], v143, s[8:9] offset:640
	v_mfma_f32_32x32x16_f16 v[2:17], v[162:165], v[166:169], v[2:17]
	s_waitcnt vmcnt(8)
	ds_write_b128 v144, v[94:97] offset:50688
	s_setprio 0
	s_waitcnt lgkmcnt(0)
	s_barrier
	s_setprio 1
	ds_read_b128 v[154:157], v147 offset:36864
	ds_read_b128 v[158:161], v146
	ds_read_b128 v[162:165], v147 offset:41472
	ds_read_b128 v[166:169], v146 offset:4608
	s_waitcnt lgkmcnt(2)
	v_mfma_f32_32x32x16_f16 v[50:65], v[154:157], v[158:161], v[50:65]
	global_load_dwordx4 v[66:69], v136, s[6:7] offset:768
	s_waitcnt lgkmcnt(1)
	v_mfma_f32_32x32x16_f16 v[34:49], v[162:165], v[158:161], v[34:49]
	ds_read_b128 v[158:161], v146 offset:32
	s_waitcnt vmcnt(8)
	ds_write_b128 v144, v[98:101] offset:18432
	s_waitcnt lgkmcnt(2)
	v_mfma_f32_32x32x16_f16 v[18:33], v[154:157], v[166:169], v[18:33]
	ds_read_b128 v[154:157], v147 offset:36896
	global_load_dwordx4 v[70:73], v140, s[8:9] offset:768
	v_mfma_f32_32x32x16_f16 v[2:17], v[162:165], v[166:169], v[2:17]
	ds_read_b128 v[162:165], v147 offset:41504
	ds_read_b128 v[166:169], v146 offset:4640
	s_waitcnt vmcnt(8)
	ds_write_b128 v144, v[102:105] offset:55296
	s_waitcnt lgkmcnt(3)
	v_mfma_f32_32x32x16_f16 v[50:65], v[154:157], v[158:161], v[50:65]
	global_load_dwordx4 v[74:77], v137, s[6:7] offset:768
	s_waitcnt lgkmcnt(2)
	v_mfma_f32_32x32x16_f16 v[34:49], v[162:165], v[158:161], v[34:49]
	ds_read_b128 v[158:161], v146 offset:64
	s_waitcnt vmcnt(8)
	ds_write_b128 v144, v[106:109] offset:23040
	s_waitcnt lgkmcnt(3)
	v_mfma_f32_32x32x16_f16 v[18:33], v[154:157], v[166:169], v[18:33]
	ds_read_b128 v[154:157], v147 offset:36928
	global_load_dwordx4 v[78:81], v141, s[8:9] offset:768
	v_mfma_f32_32x32x16_f16 v[2:17], v[162:165], v[166:169], v[2:17]
	ds_read_b128 v[162:165], v147 offset:41536
	ds_read_b128 v[166:169], v146 offset:4672
	s_waitcnt vmcnt(8)
	ds_write_b128 v144, v[110:113] offset:59904
	s_waitcnt lgkmcnt(3)
	v_mfma_f32_32x32x16_f16 v[50:65], v[154:157], v[158:161], v[50:65]
	global_load_dwordx4 v[82:85], v138, s[6:7] offset:768
	s_waitcnt lgkmcnt(2)
	v_mfma_f32_32x32x16_f16 v[34:49], v[162:165], v[158:161], v[34:49]
	ds_read_b128 v[158:161], v146 offset:96
	s_waitcnt vmcnt(8)
	ds_write_b128 v144, v[114:117] offset:27648
	s_waitcnt lgkmcnt(3)
	v_mfma_f32_32x32x16_f16 v[18:33], v[154:157], v[166:169], v[18:33]
	ds_read_b128 v[154:157], v147 offset:36960
	global_load_dwordx4 v[86:89], v142, s[8:9] offset:768
	v_mfma_f32_32x32x16_f16 v[2:17], v[162:165], v[166:169], v[2:17]
	ds_read_b128 v[162:165], v147 offset:41568
	ds_read_b128 v[166:169], v146 offset:4704
	s_waitcnt vmcnt(8)
	ds_write_b128 v144, v[118:121] offset:64512
	s_waitcnt lgkmcnt(3)
	v_mfma_f32_32x32x16_f16 v[50:65], v[154:157], v[158:161], v[50:65]
	global_load_dwordx4 v[90:93], v139, s[6:7] offset:768
	s_waitcnt lgkmcnt(2)
	v_mfma_f32_32x32x16_f16 v[34:49], v[162:165], v[158:161], v[34:49]
	s_waitcnt vmcnt(8)
	ds_write_b128 v144, v[122:125] offset:32256
	s_waitcnt lgkmcnt(2)
	v_mfma_f32_32x32x16_f16 v[18:33], v[154:157], v[166:169], v[18:33]
	global_load_dwordx4 v[94:97], v143, s[8:9] offset:768
	v_mfma_f32_32x32x16_f16 v[2:17], v[162:165], v[166:169], v[2:17]
	s_waitcnt vmcnt(8)
	ds_write_b128 v145, v[126:129] offset:64512
	s_setprio 0
	s_waitcnt lgkmcnt(0)
	s_barrier
; #define GEMM_GLOAD(P, kt_) { GEMM_GL1(P, 0, kt_) GEMM_GL1(P, 1, kt_) GEMM_GL1(P, 2, kt_) GEMM_GL1(P, 3, kt_) }
; #define GEMM_LSTORE(P, buf_) { GEMM_LS1(P, 0, buf_) GEMM_LS1(P, 1, buf_) GEMM_LS1(P, 2, buf_) GEMM_LS1(P, 3, buf_) }
; template <bool DEEP>
; DI void gemm_mainloop_t(const u16* __restrict__ Ag, int lda, const u16* __restrict__ Bg, int ldb, int K, char* ldsraw,
;                         f32x16 (&acc)[2][2], int akstep) {
;     ...
;     for (int kt = 0; kt < nk; kt += 2) {
;       if (kt + 2 < nk) GEMM_GLOAD(x, kt + 2);
;       GEMM_COMPUTE(0);
;       GEMM_LSTORE(y, 1);
;       __syncthreads();
;       if (kt + 3 < nk) GEMM_GLOAD(y, kt + 3);
;       GEMM_COMPUTE(1);
;       if (kt + 2 < nk) GEMM_LSTORE(x, 0);
;       __syncthreads();
	s_setprio 1
	ds_read_b128 v[154:157], v147 offset:55296
	ds_read_b128 v[158:161], v146 offset:18432
	ds_read_b128 v[162:165], v147 offset:59904
	ds_read_b128 v[166:169], v146 offset:23040
	s_waitcnt lgkmcnt(2)
	v_mfma_f32_32x32x16_f16 v[50:65], v[154:157], v[158:161], v[50:65]
	global_load_dwordx4 v[98:101], v136, s[6:7] offset:896
	s_waitcnt lgkmcnt(1)
	v_mfma_f32_32x32x16_f16 v[34:49], v[162:165], v[158:161], v[34:49]
	ds_read_b128 v[158:161], v146 offset:18464
	s_waitcnt vmcnt(8)
	ds_write_b128 v144, v[66:69]
	s_waitcnt lgkmcnt(2)
	v_mfma_f32_32x32x16_f16 v[18:33], v[154:157], v[166:169], v[18:33]
	ds_read_b128 v[154:157], v147 offset:55328
	global_load_dwordx4 v[102:105], v140, s[8:9] offset:896
	v_mfma_f32_32x32x16_f16 v[2:17], v[162:165], v[166:169], v[2:17]
	ds_read_b128 v[162:165], v147 offset:59936
	ds_read_b128 v[166:169], v146 offset:23072
	s_waitcnt vmcnt(8)
	ds_write_b128 v144, v[70:73] offset:36864
	s_waitcnt lgkmcnt(3)
	v_mfma_f32_32x32x16_f16 v[50:65], v[154:157], v[158:161], v[50:65]
	global_load_dwordx4 v[106:109], v137, s[6:7] offset:896
	s_waitcnt lgkmcnt(2)
	v_mfma_f32_32x32x16_f16 v[34:49], v[162:165], v[158:161], v[34:49]
	ds_read_b128 v[158:161], v146 offset:18496
	s_waitcnt vmcnt(8)
	ds_write_b128 v144, v[74:77] offset:4608
	s_waitcnt lgkmcnt(3)
	v_mfma_f32_32x32x16_f16 v[18:33], v[154:157], v[166:169], v[18:33]
	ds_read_b128 v[154:157], v147 offset:55360
	global_load_dwordx4 v[110:113], v141, s[8:9] offset:896
	v_mfma_f32_32x32x16_f16 v[2:17], v[162:165], v[166:169], v[2:17]
	ds_read_b128 v[162:165], v147 offset:59968
	ds_read_b128 v[166:169], v146 offset:23104
	s_waitcnt vmcnt(8)
	ds_write_b128 v144, v[78:81] offset:41472
	s_waitcnt lgkmcnt(3)
	v_mfma_f32_32x32x16_f16 v[50:65], v[154:157], v[158:161], v[50:65]
	global_load_dwordx4 v[114:117], v138, s[6:7] offset:896
	s_waitcnt lgkmcnt(2)
	v_mfma_f32_32x32x16_f16 v[34:49], v[162:165], v[158:161], v[34:49]
	ds_read_b128 v[158:161], v146 offset:18528
	s_waitcnt vmcnt(8)
	ds_write_b128 v144, v[82:85] offset:9216
	s_waitcnt lgkmcnt(3)
	v_mfma_f32_32x32x16_f16 v[18:33], v[154:157], v[166:169], v[18:33]
	ds_read_b128 v[154:157], v147 offset:55392
	global_load_dwordx4 v[118:121], v142, s[8:9] offset:896
	v_mfma_f32_32x32x16_f16 v[2:17], v[162:165], v[166:169], v[2:17]
	ds_read_b128 v[162:165], v147 offset:60000
	ds_read_b128 v[166:169], v146 offset:23136
	s_waitcnt vmcnt(8)
	ds_write_b128 v144, v[86:89] offset:46080
	s_waitcnt lgkmcnt(3)
	v_mfma_f32_32x32x16_f16 v[50:65], v[154:157], v[158:161], v[50:65]
	global_load_dwordx4 v[122:125], v139, s[6:7] offset:896
	s_waitcnt lgkmcnt(2)
	v_mfma_f32_32x32x16_f16 v[34:49], v[162:165], v[158:161], v[34:49]
	s_waitcnt vmcnt(8)
	ds_write_b128 v144, v[90:93] offset:13824
	s_waitcnt lgkmcnt(2)
	v_mfma_f32_32x32x16_f16 v[18:33], v[154:157], v[166:169], v[18:33]
	global_load_dwordx4 v[126:129], v143, s[8:9] offset:896
	v_mfma_f32_32x32x16_f16 v[2:17], v[162:165], v[166:169], v[2:17]
	s_waitcnt vmcnt(8)
	ds_write_b128 v144, v[94:97] offset:50688
	s_setprio 0
	s_waitcnt lgkmcnt(0)
	s_barrier
	s_setprio 1
	ds_read_b128 v[154:157], v147 offset:36864
	ds_read_b128 v[158:161], v146
	ds_read_b128 v[162:165], v147 offset:41472
	ds_read_b128 v[166:169], v146 offset:4608
	s_waitcnt lgkmcnt(2)
	v_mfma_f32_32x32x16_f16 v[50:65], v[154:157], v[158:161], v[50:65]
	global_load_dwordx4 v[66:69], v136, s[6:7] offset:1024
	s_waitcnt lgkmcnt(1)
	v_mfma_f32_32x32x16_f16 v[34:49], v[162:165], v[158:161], v[34:49]
	ds_read_b128 v[158:161], v146 offset:32
	s_waitcnt vmcnt(8)
	ds_write_b128 v144, v[98:101] offset:18432
	s_waitcnt lgkmcnt(2)
	v_mfma_f32_32x32x16_f16 v[18:33], v[154:157], v[166:169], v[18:33]
	ds_read_b128 v[154:157], v147 offset:36896
	global_load_dwordx4 v[70:73], v140, s[8:9] offset:1024
	v_mfma_f32_32x32x16_f16 v[2:17], v[162:165], v[166:169], v[2:17]
	ds_read_b128 v[162:165], v147 offset:41504
	ds_read_b128 v[166:169], v146 offset:4640
	s_waitcnt vmcnt(8)
	ds_write_b128 v144, v[102:105] offset:55296
	s_waitcnt lgkmcnt(3)
	v_mfma_f32_32x32x16_f16 v[50:65], v[154:157], v[158:161], v[50:65]
	global_load_dwordx4 v[74:77], v137, s[6:7] offset:1024
	s_waitcnt lgkmcnt(2)
	v_mfma_f32_32x32x16_f16 v[34:49], v[162:165], v[158:161], v[34:49]
	ds_read_b128 v[158:161], v146 offset:64
	s_waitcnt vmcnt(8)
	ds_write_b128 v144, v[106:109] offset:23040
	s_waitcnt lgkmcnt(3)
	v_mfma_f32_32x32x16_f16 v[18:33], v[154:157], v[166:169], v[18:33]
	ds_read_b128 v[154:157], v147 offset:36928
	global_load_dwordx4 v[78:81], v141, s[8:9] offset:1024
	v_mfma_f32_32x32x16_f16 v[2:17], v[162:165], v[166:169], v[2:17]
	ds_read_b128 v[162:165], v147 offset:41536
	ds_read_b128 v[166:169], v146 offset:4672
	s_waitcnt vmcnt(8)
	ds_write_b128 v144, v[110:113] offset:59904
	s_waitcnt lgkmcnt(3)
	v_mfma_f32_32x32x16_f16 v[50:65], v[154:157], v[158:161], v[50:65]
	global_load_dwordx4 v[82:85], v138, s[6:7] offset:1024
	s_waitcnt lgkmcnt(2)
	v_mfma_f32_32x32x16_f16 v[34:49], v[162:165], v[158:161], v[34:49]
	ds_read_b128 v[158:161], v146 offset:96
	s_waitcnt vmcnt(8)
	ds_write_b128 v144, v[114:117] offset:27648
	s_waitcnt lgkmcnt(3)
	v_mfma_f32_32x32x16_f16 v[18:33], v[154:157], v[166:169], v[18:33]
	ds_read_b128 v[154:157], v147 offset:36960
	global_load_dwordx4 v[86:89], v142, s[8:9] offset:1024
	v_mfma_f32_32x32x16_f16 v[2:17], v[162:165], v[166:169], v[2:17]
	ds_read_b128 v[162:165], v147 offset:41568
	ds_read_b128 v[166:169], v146 offset:4704
	s_waitcnt vmcnt(8)
	ds_write_b128 v144, v[118:121] offset:64512
	s_waitcnt lgkmcnt(3)
	v_mfma_f32_32x32x16_f16 v[50:65], v[154:157], v[158:161], v[50:65]
	global_load_dwordx4 v[90:93], v139, s[6:7] offset:1024
	s_waitcnt lgkmcnt(2)
	v_mfma_f32_32x32x16_f16 v[34:49], v[162:165], v[158:161], v[34:49]
	s_waitcnt vmcnt(8)
	ds_write_b128 v144, v[122:125] offset:32256
	s_waitcnt lgkmcnt(2)
	v_mfma_f32_32x32x16_f16 v[18:33], v[154:157], v[166:169], v[18:33]
	global_load_dwordx4 v[94:97], v143, s[8:9] offset:1024
	v_mfma_f32_32x32x16_f16 v[2:17], v[162:165], v[166:169], v[2:17]
	s_waitcnt vmcnt(8)
	ds_write_b128 v145, v[126:129] offset:64512
	s_setprio 0
	s_waitcnt lgkmcnt(0)
	s_barrier
; #define GEMM_GLOAD(P, kt_) { GEMM_GL1(P, 0, kt_) GEMM_GL1(P, 1, kt_) GEMM_GL1(P, 2, kt_) GEMM_GL1(P, 3, kt_) }
; #define GEMM_LSTORE(P, buf_) { GEMM_LS1(P, 0, buf_) GEMM_LS1(P, 1, buf_) GEMM_LS1(P, 2, buf_) GEMM_LS1(P, 3, buf_) }
; template <bool DEEP>
; DI void gemm_mainloop_t(const u16* __restrict__ Ag, int lda, const u16* __restrict__ Bg, int ldb, int K, char* ldsraw,
;                         f32x16 (&acc)[2][2], int akstep) {
;     ...
;   if (DEEP) {
;     uint4 ya0, ya1, ya2, ya3, yb0, yb1, yb2, yb3;
;     GEMM_GLOAD(x, 0);
;     GEMM_GLOAD(y, 1);
;     GEMM_LSTORE(x, 0);
;     __syncthreads();
;     for (int kt = 0; kt < nk; kt += 2) {
;       if (kt + 2 < nk) GEMM_GLOAD(x, kt + 2);
;       GEMM_COMPUTE(0);
;       GEMM_LSTORE(y, 1);
;       __syncthreads();
;       if (kt + 3 < nk) GEMM_GLOAD(y, kt + 3);
;       GEMM_COMPUTE(1);
;       if (kt + 2 < nk) GEMM_LSTORE(x, 0);
;       __syncthreads();
;     }
	s_setprio 1
	ds_read_b128 v[154:157], v147 offset:55296
	ds_read_b128 v[158:161], v146 offset:18432
	ds_read_b128 v[162:165], v147 offset:59904
	ds_read_b128 v[166:169], v146 offset:23040
	s_waitcnt lgkmcnt(2)
	v_mfma_f32_32x32x16_f16 v[50:65], v[154:157], v[158:161], v[50:65]
	global_load_dwordx4 v[98:101], v136, s[6:7] offset:1152
	s_waitcnt lgkmcnt(1)
	v_mfma_f32_32x32x16_f16 v[34:49], v[162:165], v[158:161], v[34:49]
	ds_read_b128 v[158:161], v146 offset:18464
	s_waitcnt vmcnt(8)
	ds_write_b128 v144, v[66:69]
	s_waitcnt lgkmcnt(2)
	v_mfma_f32_32x32x16_f16 v[18:33], v[154:157], v[166:169], v[18:33]
	ds_read_b128 v[154:157], v147 offset:55328
	global_load_dwordx4 v[102:105], v140, s[8:9] offset:1152
	v_mfma_f32_32x32x16_f16 v[2:17], v[162:165], v[166:169], v[2:17]
	ds_read_b128 v[162:165], v147 offset:59936
	ds_read_b128 v[166:169], v146 offset:23072
	s_waitcnt vmcnt(8)
	ds_write_b128 v144, v[70:73] offset:36864
	s_waitcnt lgkmcnt(3)
	v_mfma_f32_32x32x16_f16 v[50:65], v[154:157], v[158:161], v[50:65]
	global_load_dwordx4 v[106:109], v137, s[6:7] offset:1152
	s_waitcnt lgkmcnt(2)
	v_mfma_f32_32x32x16_f16 v[34:49], v[162:165], v[158:161], v[34:49]
	ds_read_b128 v[158:161], v146 offset:18496
	s_waitcnt vmcnt(8)
	ds_write_b128 v144, v[74:77] offset:4608
	s_waitcnt lgkmcnt(3)
	v_mfma_f32_32x32x16_f16 v[18:33], v[154:157], v[166:169], v[18:33]
	ds_read_b128 v[154:157], v147 offset:55360
	global_load_dwordx4 v[110:113], v141, s[8:9] offset:1152
	v_mfma_f32_32x32x16_f16 v[2:17], v[162:165], v[166:169], v[2:17]
	ds_read_b128 v[162:165], v147 offset:59968
	ds_read_b128 v[166:169], v146 offset:23104
	s_waitcnt vmcnt(8)
	ds_write_b128 v144, v[78:81] offset:41472
	s_waitcnt lgkmcnt(3)
	v_mfma_f32_32x32x16_f16 v[50:65], v[154:157], v[158:161], v[50:65]
	global_load_dwordx4 v[114:117], v138, s[6:7] offset:1152
	s_waitcnt lgkmcnt(2)
	v_mfma_f32_32x32x16_f16 v[34:49], v[162:165], v[158:161], v[34:49]
	ds_read_b128 v[158:161], v146 offset:18528
	s_waitcnt vmcnt(8)
	ds_write_b128 v144, v[82:85] offset:9216
	s_waitcnt lgkmcnt(3)
	v_mfma_f32_32x32x16_f16 v[18:33], v[154:157], v[166:169], v[18:33]
	ds_read_b128 v[154:157], v147 offset:55392
	global_load_dwordx4 v[118:121], v142, s[8:9] offset:1152
	v_mfma_f32_32x32x16_f16 v[2:17], v[162:165], v[166:169], v[2:17]
	ds_read_b128 v[162:165], v147 offset:60000
	ds_read_b128 v[166:169], v146 offset:23136
	s_waitcnt vmcnt(8)
	ds_write_b128 v144, v[86:89] offset:46080
	s_waitcnt lgkmcnt(3)
	v_mfma_f32_32x32x16_f16 v[50:65], v[154:157], v[158:161], v[50:65]
	global_load_dwordx4 v[122:125], v139, s[6:7] offset:1152
	s_waitcnt lgkmcnt(2)
	v_mfma_f32_32x32x16_f16 v[34:49], v[162:165], v[158:161], v[34:49]
	s_waitcnt vmcnt(8)
	ds_write_b128 v144, v[90:93] offset:13824
	s_waitcnt lgkmcnt(2)
	v_mfma_f32_32x32x16_f16 v[18:33], v[154:157], v[166:169], v[18:33]
	global_load_dwordx4 v[126:129], v143, s[8:9] offset:1152
	v_mfma_f32_32x32x16_f16 v[2:17], v[162:165], v[166:169], v[2:17]
	s_waitcnt vmcnt(8)
	ds_write_b128 v144, v[94:97] offset:50688
	s_setprio 0
	s_waitcnt lgkmcnt(0)
	s_barrier
	s_setprio 1
	ds_read_b128 v[154:157], v147 offset:36864
	ds_read_b128 v[158:161], v146
	ds_read_b128 v[162:165], v147 offset:41472
	ds_read_b128 v[166:169], v146 offset:4608
	s_waitcnt lgkmcnt(2)
	v_mfma_f32_32x32x16_f16 v[50:65], v[154:157], v[158:161], v[50:65]
	global_load_dwordx4 v[66:69], v136, s[6:7] offset:1280
	s_waitcnt lgkmcnt(1)
	v_mfma_f32_32x32x16_f16 v[34:49], v[162:165], v[158:161], v[34:49]
	ds_read_b128 v[158:161], v146 offset:32
	s_waitcnt vmcnt(8)
	ds_write_b128 v144, v[98:101] offset:18432
	s_waitcnt lgkmcnt(2)
	v_mfma_f32_32x32x16_f16 v[18:33], v[154:157], v[166:169], v[18:33]
	ds_read_b128 v[154:157], v147 offset:36896
	global_load_dwordx4 v[70:73], v140, s[8:9] offset:1280
	v_mfma_f32_32x32x16_f16 v[2:17], v[162:165], v[166:169], v[2:17]
	ds_read_b128 v[162:165], v147 offset:41504
	ds_read_b128 v[166:169], v146 offset:4640
	s_waitcnt vmcnt(8)
	ds_write_b128 v144, v[102:105] offset:55296
	s_waitcnt lgkmcnt(3)
	v_mfma_f32_32x32x16_f16 v[50:65], v[154:157], v[158:161], v[50:65]
	global_load_dwordx4 v[74:77], v137, s[6:7] offset:1280
	s_waitcnt lgkmcnt(2)
	v_mfma_f32_32x32x16_f16 v[34:49], v[162:165], v[158:161], v[34:49]
	ds_read_b128 v[158:161], v146 offset:64
	s_waitcnt vmcnt(8)
	ds_write_b128 v144, v[106:109] offset:23040
	s_waitcnt lgkmcnt(3)
	v_mfma_f32_32x32x16_f16 v[18:33], v[154:157], v[166:169], v[18:33]
	ds_read_b128 v[154:157], v147 offset:36928
	global_load_dwordx4 v[78:81], v141, s[8:9] offset:1280
	v_mfma_f32_32x32x16_f16 v[2:17], v[162:165], v[166:169], v[2:17]
	ds_read_b128 v[162:165], v147 offset:41536
	ds_read_b128 v[166:169], v146 offset:4672
	s_waitcnt vmcnt(8)
	ds_write_b128 v144, v[110:113] offset:59904
	s_waitcnt lgkmcnt(3)
	v_mfma_f32_32x32x16_f16 v[50:65], v[154:157], v[158:161], v[50:65]
	global_load_dwordx4 v[82:85], v138, s[6:7] offset:1280
	s_waitcnt lgkmcnt(2)
	v_mfma_f32_32x32x16_f16 v[34:49], v[162:165], v[158:161], v[34:49]
	ds_read_b128 v[158:161], v146 offset:96
	s_waitcnt vmcnt(8)
	ds_write_b128 v144, v[114:117] offset:27648
	s_waitcnt lgkmcnt(3)
	v_mfma_f32_32x32x16_f16 v[18:33], v[154:157], v[166:169], v[18:33]
	ds_read_b128 v[154:157], v147 offset:36960
	global_load_dwordx4 v[86:89], v142, s[8:9] offset:1280
	v_mfma_f32_32x32x16_f16 v[2:17], v[162:165], v[166:169], v[2:17]
	ds_read_b128 v[162:165], v147 offset:41568
	ds_read_b128 v[166:169], v146 offset:4704
	s_waitcnt vmcnt(8)
	ds_write_b128 v144, v[118:121] offset:64512
	s_waitcnt lgkmcnt(3)
	v_mfma_f32_32x32x16_f16 v[50:65], v[154:157], v[158:161], v[50:65]
	global_load_dwordx4 v[90:93], v139, s[6:7] offset:1280
	s_waitcnt lgkmcnt(2)
	v_mfma_f32_32x32x16_f16 v[34:49], v[162:165], v[158:161], v[34:49]
	s_waitcnt vmcnt(8)
	ds_write_b128 v144, v[122:125] offset:32256
	s_waitcnt lgkmcnt(2)
	v_mfma_f32_32x32x16_f16 v[18:33], v[154:157], v[166:169], v[18:33]
	global_load_dwordx4 v[94:97], v143, s[8:9] offset:1280
	v_mfma_f32_32x32x16_f16 v[2:17], v[162:165], v[166:169], v[2:17]
	s_waitcnt vmcnt(8)
	ds_write_b128 v145, v[126:129] offset:64512
	s_setprio 0
	s_waitcnt lgkmcnt(0)
	s_barrier
; #define GEMM_GLOAD(P, kt_) { GEMM_GL1(P, 0, kt_) GEMM_GL1(P, 1, kt_) GEMM_GL1(P, 2, kt_) GEMM_GL1(P, 3, kt_) }
; #define GEMM_LSTORE(P, buf_) { GEMM_LS1(P, 0, buf_) GEMM_LS1(P, 1, buf_) GEMM_LS1(P, 2, buf_) GEMM_LS1(P, 3, buf_) }
; template <bool DEEP>
; DI void gemm_mainloop_t(const u16* __restrict__ Ag, int lda, const u16* __restrict__ Bg, int ldb, int K, char* ldsraw,
;                         f32x16 (&acc)[2][2], int akstep) {
;     ...
;   if (DEEP) {
;     uint4 ya0, ya1, ya2, ya3, yb0, yb1, yb2, yb3;
;     GEMM_GLOAD(x, 0);
;     GEMM_GLOAD(y, 1);
;     GEMM_LSTORE(x, 0);
;     __syncthreads();
;     for (int kt = 0; kt < nk; kt += 2) {
;       if (kt + 2 < nk) GEMM_GLOAD(x, kt + 2);
;       GEMM_COMPUTE(0);
;       GEMM_LSTORE(y, 1);
;       __syncthreads();
;       if (kt + 3 < nk) GEMM_GLOAD(y, kt + 3);
;       GEMM_COMPUTE(1);
;       if (kt + 2 < nk) GEMM_LSTORE(x, 0);
;       __syncthreads();
;     }
	s_setprio 1
	ds_read_b128 v[154:157], v147 offset:55296
	ds_read_b128 v[158:161], v146 offset:18432
	ds_read_b128 v[162:165], v147 offset:59904
	ds_read_b128 v[166:169], v146 offset:23040
	s_waitcnt lgkmcnt(2)
	v_mfma_f32_32x32x16_f16 v[50:65], v[154:157], v[158:161], v[50:65]
	global_load_dwordx4 v[98:101], v136, s[6:7] offset:1408
	s_waitcnt lgkmcnt(1)
	v_mfma_f32_32x32x16_f16 v[34:49], v[162:165], v[158:161], v[34:49]
	ds_read_b128 v[158:161], v146 offset:18464
	s_waitcnt vmcnt(8)
	ds_write_b128 v144, v[66:69]
	s_waitcnt lgkmcnt(2)
	v_mfma_f32_32x32x16_f16 v[18:33], v[154:157], v[166:169], v[18:33]
	ds_read_b128 v[154:157], v147 offset:55328
	global_load_dwordx4 v[102:105], v140, s[8:9] offset:1408
	v_mfma_f32_32x32x16_f16 v[2:17], v[162:165], v[166:169], v[2:17]
	ds_read_b128 v[162:165], v147 offset:59936
	ds_read_b128 v[166:169], v146 offset:23072
	s_waitcnt vmcnt(8)
	ds_write_b128 v144, v[70:73] offset:36864
	s_waitcnt lgkmcnt(3)
	v_mfma_f32_32x32x16_f16 v[50:65], v[154:157], v[158:161], v[50:65]
	global_load_dwordx4 v[106:109], v137, s[6:7] offset:1408
	s_waitcnt lgkmcnt(2)
	v_mfma_f32_32x32x16_f16 v[34:49], v[162:165], v[158:161], v[34:49]
	ds_read_b128 v[158:161], v146 offset:18496
	s_waitcnt vmcnt(8)
	ds_write_b128 v144, v[74:77] offset:4608
	s_waitcnt lgkmcnt(3)
	v_mfma_f32_32x32x16_f16 v[18:33], v[154:157], v[166:169], v[18:33]
	ds_read_b128 v[154:157], v147 offset:55360
	global_load_dwordx4 v[110:113], v141, s[8:9] offset:1408
	v_mfma_f32_32x32x16_f16 v[2:17], v[162:165], v[166:169], v[2:17]
	ds_read_b128 v[162:165], v147 offset:59968
	ds_read_b128 v[166:169], v146 offset:23104
	s_waitcnt vmcnt(8)
	ds_write_b128 v144, v[78:81] offset:41472
	s_waitcnt lgkmcnt(3)
	v_mfma_f32_32x32x16_f16 v[50:65], v[154:157], v[158:161], v[50:65]
	global_load_dwordx4 v[114:117], v138, s[6:7] offset:1408
	s_waitcnt lgkmcnt(2)
	v_mfma_f32_32x32x16_f16 v[34:49], v[162:165], v[158:161], v[34:49]
	ds_read_b128 v[158:161], v146 offset:18528
	s_waitcnt vmcnt(8)
	ds_write_b128 v144, v[82:85] offset:9216
	s_waitcnt lgkmcnt(3)
	v_mfma_f32_32x32x16_f16 v[18:33], v[154:157], v[166:169], v[18:33]
	ds_read_b128 v[154:157], v147 offset:55392
	global_load_dwordx4 v[118:121], v142, s[8:9] offset:1408
	v_mfma_f32_32x32x16_f16 v[2:17], v[162:165], v[166:169], v[2:17]
	ds_read_b128 v[162:165], v147 offset:60000
	ds_read_b128 v[166:169], v146 offset:23136
	s_waitcnt vmcnt(8)
	ds_write_b128 v144, v[86:89] offset:46080
	s_waitcnt lgkmcnt(3)
	v_mfma_f32_32x32x16_f16 v[50:65], v[154:157], v[158:161], v[50:65]
	global_load_dwordx4 v[122:125], v139, s[6:7] offset:1408
	s_waitcnt lgkmcnt(2)
	v_mfma_f32_32x32x16_f16 v[34:49], v[162:165], v[158:161], v[34:49]
	s_waitcnt vmcnt(8)
	ds_write_b128 v144, v[90:93] offset:13824
	s_waitcnt lgkmcnt(2)
	v_mfma_f32_32x32x16_f16 v[18:33], v[154:157], v[166:169], v[18:33]
	global_load_dwordx4 v[126:129], v143, s[8:9] offset:1408
	v_mfma_f32_32x32x16_f16 v[2:17], v[162:165], v[166:169], v[2:17]
	s_waitcnt vmcnt(8)
	ds_write_b128 v144, v[94:97] offset:50688
	s_setprio 0
	s_waitcnt lgkmcnt(0)
	s_barrier
	s_setprio 1
	ds_read_b128 v[154:157], v147 offset:36864
	ds_read_b128 v[158:161], v146
	ds_read_b128 v[162:165], v147 offset:41472
	ds_read_b128 v[166:169], v146 offset:4608
	s_waitcnt lgkmcnt(2)
	v_mfma_f32_32x32x16_f16 v[50:65], v[154:157], v[158:161], v[50:65]
	global_load_dwordx4 v[66:69], v136, s[6:7] offset:1536
	s_waitcnt lgkmcnt(1)
	v_mfma_f32_32x32x16_f16 v[34:49], v[162:165], v[158:161], v[34:49]
	ds_read_b128 v[158:161], v146 offset:32
	s_waitcnt vmcnt(8)
	ds_write_b128 v144, v[98:101] offset:18432
	s_waitcnt lgkmcnt(2)
	v_mfma_f32_32x32x16_f16 v[18:33], v[154:157], v[166:169], v[18:33]
	ds_read_b128 v[154:157], v147 offset:36896
	global_load_dwordx4 v[70:73], v140, s[8:9] offset:1536
	v_mfma_f32_32x32x16_f16 v[2:17], v[162:165], v[166:169], v[2:17]
	ds_read_b128 v[162:165], v147 offset:41504
	ds_read_b128 v[166:169], v146 offset:4640
	s_waitcnt vmcnt(8)
	ds_write_b128 v144, v[102:105] offset:55296
	s_waitcnt lgkmcnt(3)
	v_mfma_f32_32x32x16_f16 v[50:65], v[154:157], v[158:161], v[50:65]
	global_load_dwordx4 v[74:77], v137, s[6:7] offset:1536
	s_waitcnt lgkmcnt(2)
	v_mfma_f32_32x32x16_f16 v[34:49], v[162:165], v[158:161], v[34:49]
	ds_read_b128 v[158:161], v146 offset:64
	s_waitcnt vmcnt(8)
	ds_write_b128 v144, v[106:109] offset:23040
	s_waitcnt lgkmcnt(3)
	v_mfma_f32_32x32x16_f16 v[18:33], v[154:157], v[166:169], v[18:33]
	ds_read_b128 v[154:157], v147 offset:36928
	global_load_dwordx4 v[78:81], v141, s[8:9] offset:1536
	v_mfma_f32_32x32x16_f16 v[2:17], v[162:165], v[166:169], v[2:17]
	ds_read_b128 v[162:165], v147 offset:41536
	ds_read_b128 v[166:169], v146 offset:4672
	s_waitcnt vmcnt(8)
	ds_write_b128 v144, v[110:113] offset:59904
	s_waitcnt lgkmcnt(3)
	v_mfma_f32_32x32x16_f16 v[50:65], v[154:157], v[158:161], v[50:65]
	global_load_dwordx4 v[82:85], v138, s[6:7] offset:1536
	s_waitcnt lgkmcnt(2)
	v_mfma_f32_32x32x16_f16 v[34:49], v[162:165], v[158:161], v[34:49]
	ds_read_b128 v[158:161], v146 offset:96
	s_waitcnt vmcnt(8)
	ds_write_b128 v144, v[114:117] offset:27648
	s_waitcnt lgkmcnt(3)
	v_mfma_f32_32x32x16_f16 v[18:33], v[154:157], v[166:169], v[18:33]
	ds_read_b128 v[154:157], v147 offset:36960
	global_load_dwordx4 v[86:89], v142, s[8:9] offset:1536
	v_mfma_f32_32x32x16_f16 v[2:17], v[162:165], v[166:169], v[2:17]
	ds_read_b128 v[162:165], v147 offset:41568
	ds_read_b128 v[166:169], v146 offset:4704
	s_waitcnt vmcnt(8)
	ds_write_b128 v144, v[118:121] offset:64512
	s_waitcnt lgkmcnt(3)
	v_mfma_f32_32x32x16_f16 v[50:65], v[154:157], v[158:161], v[50:65]
	global_load_dwordx4 v[90:93], v139, s[6:7] offset:1536
	s_waitcnt lgkmcnt(2)
	v_mfma_f32_32x32x16_f16 v[34:49], v[162:165], v[158:161], v[34:49]
	s_waitcnt vmcnt(8)
	ds_write_b128 v144, v[122:125] offset:32256
	s_waitcnt lgkmcnt(2)
	v_mfma_f32_32x32x16_f16 v[18:33], v[154:157], v[166:169], v[18:33]
	global_load_dwordx4 v[94:97], v143, s[8:9] offset:1536
	v_mfma_f32_32x32x16_f16 v[2:17], v[162:165], v[166:169], v[2:17]
	s_waitcnt vmcnt(8)
	ds_write_b128 v145, v[126:129] offset:64512
	s_setprio 0
	s_waitcnt lgkmcnt(0)
	s_barrier
; #define GEMM_GLOAD(P, kt_) { GEMM_GL1(P, 0, kt_) GEMM_GL1(P, 1, kt_) GEMM_GL1(P, 2, kt_) GEMM_GL1(P, 3, kt_) }
; #define GEMM_LSTORE(P, buf_) { GEMM_LS1(P, 0, buf_) GEMM_LS1(P, 1, buf_) GEMM_LS1(P, 2, buf_) GEMM_LS1(P, 3, buf_) }
; template <bool DEEP>
; DI void gemm_mainloop_t(const u16* __restrict__ Ag, int lda, const u16* __restrict__ Bg, int ldb, int K, char* ldsraw,
;                         f32x16 (&acc)[2][2], int akstep) {
;     ...
;   if (DEEP) {
;     uint4 ya0, ya1, ya2, ya3, yb0, yb1, yb2, yb3;
;     GEMM_GLOAD(x, 0);
;     GEMM_GLOAD(y, 1);
;     GEMM_LSTORE(x, 0);
;     __syncthreads();
;     for (int kt = 0; kt < nk; kt += 2) {
;       if (kt + 2 < nk) GEMM_GLOAD(x, kt + 2);
;       GEMM_COMPUTE(0);
;       GEMM_LSTORE(y, 1);
;       __syncthreads();
;       if (kt + 3 < nk) GEMM_GLOAD(y, kt + 3);
;       GEMM_COMPUTE(1);
;       if (kt + 2 < nk) GEMM_LSTORE(x, 0);
;       __syncthreads();
;     }
	s_setprio 1
	ds_read_b128 v[154:157], v147 offset:55296
	ds_read_b128 v[158:161], v146 offset:18432
	ds_read_b128 v[162:165], v147 offset:59904
	ds_read_b128 v[166:169], v146 offset:23040
	s_waitcnt lgkmcnt(2)
	v_mfma_f32_32x32x16_f16 v[50:65], v[154:157], v[158:161], v[50:65]
	global_load_dwordx4 v[98:101], v136, s[6:7] offset:1664
	s_waitcnt lgkmcnt(1)
	v_mfma_f32_32x32x16_f16 v[34:49], v[162:165], v[158:161], v[34:49]
	ds_read_b128 v[158:161], v146 offset:18464
	s_waitcnt vmcnt(8)
	ds_write_b128 v144, v[66:69]
	s_waitcnt lgkmcnt(2)
	v_mfma_f32_32x32x16_f16 v[18:33], v[154:157], v[166:169], v[18:33]
	ds_read_b128 v[154:157], v147 offset:55328
	global_load_dwordx4 v[102:105], v140, s[8:9] offset:1664
	v_mfma_f32_32x32x16_f16 v[2:17], v[162:165], v[166:169], v[2:17]
	ds_read_b128 v[162:165], v147 offset:59936
	ds_read_b128 v[166:169], v146 offset:23072
	s_waitcnt vmcnt(8)
	ds_write_b128 v144, v[70:73] offset:36864
	s_waitcnt lgkmcnt(3)
	v_mfma_f32_32x32x16_f16 v[50:65], v[154:157], v[158:161], v[50:65]
	global_load_dwordx4 v[106:109], v137, s[6:7] offset:1664
	s_waitcnt lgkmcnt(2)
	v_mfma_f32_32x32x16_f16 v[34:49], v[162:165], v[158:161], v[34:49]
	ds_read_b128 v[158:161], v146 offset:18496
	s_waitcnt vmcnt(8)
	ds_write_b128 v144, v[74:77] offset:4608
	s_waitcnt lgkmcnt(3)
	v_mfma_f32_32x32x16_f16 v[18:33], v[154:157], v[166:169], v[18:33]
	ds_read_b128 v[154:157], v147 offset:55360
	global_load_dwordx4 v[110:113], v141, s[8:9] offset:1664
	v_mfma_f32_32x32x16_f16 v[2:17], v[162:165], v[166:169], v[2:17]
	ds_read_b128 v[162:165], v147 offset:59968
	ds_read_b128 v[166:169], v146 offset:23104
	s_waitcnt vmcnt(8)
	ds_write_b128 v144, v[78:81] offset:41472
	s_waitcnt lgkmcnt(3)
	v_mfma_f32_32x32x16_f16 v[50:65], v[154:157], v[158:161], v[50:65]
	global_load_dwordx4 v[114:117], v138, s[6:7] offset:1664
	s_waitcnt lgkmcnt(2)
	v_mfma_f32_32x32x16_f16 v[34:49], v[162:165], v[158:161], v[34:49]
	ds_read_b128 v[158:161], v146 offset:18528
	s_waitcnt vmcnt(8)
	ds_write_b128 v144, v[82:85] offset:9216
	s_waitcnt lgkmcnt(3)
	v_mfma_f32_32x32x16_f16 v[18:33], v[154:157], v[166:169], v[18:33]
	ds_read_b128 v[154:157], v147 offset:55392
	global_load_dwordx4 v[118:121], v142, s[8:9] offset:1664
	v_mfma_f32_32x32x16_f16 v[2:17], v[162:165], v[166:169], v[2:17]
	ds_read_b128 v[162:165], v147 offset:60000
	ds_read_b128 v[166:169], v146 offset:23136
	s_waitcnt vmcnt(8)
	ds_write_b128 v144, v[86:89] offset:46080
	s_waitcnt lgkmcnt(3)
	v_mfma_f32_32x32x16_f16 v[50:65], v[154:157], v[158:161], v[50:65]
	global_load_dwordx4 v[122:125], v139, s[6:7] offset:1664
	s_waitcnt lgkmcnt(2)
	v_mfma_f32_32x32x16_f16 v[34:49], v[162:165], v[158:161], v[34:49]
	s_waitcnt vmcnt(8)
	ds_write_b128 v144, v[90:93] offset:13824
	s_waitcnt lgkmcnt(2)
	v_mfma_f32_32x32x16_f16 v[18:33], v[154:157], v[166:169], v[18:33]
	global_load_dwordx4 v[126:129], v143, s[8:9] offset:1664
	v_mfma_f32_32x32x16_f16 v[2:17], v[162:165], v[166:169], v[2:17]
	s_waitcnt vmcnt(8)
	ds_write_b128 v144, v[94:97] offset:50688
	s_setprio 0
	s_waitcnt lgkmcnt(0)
	s_barrier
	s_setprio 1
	ds_read_b128 v[154:157], v147 offset:36864
	ds_read_b128 v[158:161], v146
	ds_read_b128 v[162:165], v147 offset:41472
	ds_read_b128 v[166:169], v146 offset:4608
	s_waitcnt lgkmcnt(2)
	v_mfma_f32_32x32x16_f16 v[50:65], v[154:157], v[158:161], v[50:65]
	global_load_dwordx4 v[66:69], v136, s[6:7] offset:1792
	s_waitcnt lgkmcnt(1)
	v_mfma_f32_32x32x16_f16 v[34:49], v[162:165], v[158:161], v[34:49]
	ds_read_b128 v[158:161], v146 offset:32
	s_waitcnt vmcnt(8)
	ds_write_b128 v144, v[98:101] offset:18432
	s_waitcnt lgkmcnt(2)
	v_mfma_f32_32x32x16_f16 v[18:33], v[154:157], v[166:169], v[18:33]
	ds_read_b128 v[154:157], v147 offset:36896
	global_load_dwordx4 v[70:73], v140, s[8:9] offset:1792
	v_mfma_f32_32x32x16_f16 v[2:17], v[162:165], v[166:169], v[2:17]
	ds_read_b128 v[162:165], v147 offset:41504
	ds_read_b128 v[166:169], v146 offset:4640
	s_waitcnt vmcnt(8)
	ds_write_b128 v144, v[102:105] offset:55296
	s_waitcnt lgkmcnt(3)
	v_mfma_f32_32x32x16_f16 v[50:65], v[154:157], v[158:161], v[50:65]
	global_load_dwordx4 v[74:77], v137, s[6:7] offset:1792
	s_waitcnt lgkmcnt(2)
	v_mfma_f32_32x32x16_f16 v[34:49], v[162:165], v[158:161], v[34:49]
	ds_read_b128 v[158:161], v146 offset:64
	s_waitcnt vmcnt(8)
	ds_write_b128 v144, v[106:109] offset:23040
	s_waitcnt lgkmcnt(3)
	v_mfma_f32_32x32x16_f16 v[18:33], v[154:157], v[166:169], v[18:33]
	ds_read_b128 v[154:157], v147 offset:36928
	global_load_dwordx4 v[78:81], v141, s[8:9] offset:1792
	v_mfma_f32_32x32x16_f16 v[2:17], v[162:165], v[166:169], v[2:17]
	ds_read_b128 v[162:165], v147 offset:41536
	ds_read_b128 v[166:169], v146 offset:4672
	s_waitcnt vmcnt(8)
	ds_write_b128 v144, v[110:113] offset:59904
	s_waitcnt lgkmcnt(3)
	v_mfma_f32_32x32x16_f16 v[50:65], v[154:157], v[158:161], v[50:65]
	global_load_dwordx4 v[82:85], v138, s[6:7] offset:1792
	s_waitcnt lgkmcnt(2)
	v_mfma_f32_32x32x16_f16 v[34:49], v[162:165], v[158:161], v[34:49]
	ds_read_b128 v[158:161], v146 offset:96
	s_waitcnt vmcnt(8)
	ds_write_b128 v144, v[114:117] offset:27648
	s_waitcnt lgkmcnt(3)
	v_mfma_f32_32x32x16_f16 v[18:33], v[154:157], v[166:169], v[18:33]
	ds_read_b128 v[154:157], v147 offset:36960
	global_load_dwordx4 v[86:89], v142, s[8:9] offset:1792
	v_mfma_f32_32x32x16_f16 v[2:17], v[162:165], v[166:169], v[2:17]
	ds_read_b128 v[162:165], v147 offset:41568
	ds_read_b128 v[166:169], v146 offset:4704
	s_waitcnt vmcnt(8)
	ds_write_b128 v144, v[118:121] offset:64512
	s_waitcnt lgkmcnt(3)
	v_mfma_f32_32x32x16_f16 v[50:65], v[154:157], v[158:161], v[50:65]
	global_load_dwordx4 v[90:93], v139, s[6:7] offset:1792
	s_waitcnt lgkmcnt(2)
	v_mfma_f32_32x32x16_f16 v[34:49], v[162:165], v[158:161], v[34:49]
	s_waitcnt vmcnt(8)
	ds_write_b128 v144, v[122:125] offset:32256
	s_waitcnt lgkmcnt(2)
	v_mfma_f32_32x32x16_f16 v[18:33], v[154:157], v[166:169], v[18:33]
	global_load_dwordx4 v[94:97], v143, s[8:9] offset:1792
	v_mfma_f32_32x32x16_f16 v[2:17], v[162:165], v[166:169], v[2:17]
	s_waitcnt vmcnt(8)
	ds_write_b128 v145, v[126:129] offset:64512
	s_setprio 0
	s_waitcnt lgkmcnt(0)
	s_barrier
; #define GEMM_GLOAD(P, kt_) { GEMM_GL1(P, 0, kt_) GEMM_GL1(P, 1, kt_) GEMM_GL1(P, 2, kt_) GEMM_GL1(P, 3, kt_) }
; #define GEMM_LSTORE(P, buf_) { GEMM_LS1(P, 0, buf_) GEMM_LS1(P, 1, buf_) GEMM_LS1(P, 2, buf_) GEMM_LS1(P, 3, buf_) }
; template <bool DEEP>
; DI void gemm_mainloop_t(const u16* __restrict__ Ag, int lda, const u16* __restrict__ Bg, int ldb, int K, char* ldsraw,
;                         f32x16 (&acc)[2][2], int akstep) {
;     ...
;   if (DEEP) {
;     uint4 ya0, ya1, ya2, ya3, yb0, yb1, yb2, yb3;
;     GEMM_GLOAD(x, 0);
;     GEMM_GLOAD(y, 1);
;     GEMM_LSTORE(x, 0);
;     __syncthreads();
;     for (int kt = 0; kt < nk; kt += 2) {
;       if (kt + 2 < nk) GEMM_GLOAD(x, kt + 2);
;       GEMM_COMPUTE(0);
;       GEMM_LSTORE(y, 1);
;       __syncthreads();
;       if (kt + 3 < nk) GEMM_GLOAD(y, kt + 3);
;       GEMM_COMPUTE(1);
;       if (kt + 2 < nk) GEMM_LSTORE(x, 0);
;       __syncthreads();
;     }
	s_setprio 1
	ds_read_b128 v[154:157], v147 offset:55296
	ds_read_b128 v[158:161], v146 offset:18432
	ds_read_b128 v[162:165], v147 offset:59904
	ds_read_b128 v[166:169], v146 offset:23040
	s_waitcnt lgkmcnt(2)
	v_mfma_f32_32x32x16_f16 v[50:65], v[154:157], v[158:161], v[50:65]
	global_load_dwordx4 v[98:101], v136, s[6:7] offset:1920
	s_waitcnt lgkmcnt(1)
	v_mfma_f32_32x32x16_f16 v[34:49], v[162:165], v[158:161], v[34:49]
	ds_read_b128 v[158:161], v146 offset:18464
	s_waitcnt vmcnt(8)
	ds_write_b128 v144, v[66:69]
	s_waitcnt lgkmcnt(2)
	v_mfma_f32_32x32x16_f16 v[18:33], v[154:157], v[166:169], v[18:33]
	ds_read_b128 v[154:157], v147 offset:55328
	global_load_dwordx4 v[102:105], v140, s[8:9] offset:1920
	v_mfma_f32_32x32x16_f16 v[2:17], v[162:165], v[166:169], v[2:17]
	ds_read_b128 v[162:165], v147 offset:59936
	ds_read_b128 v[166:169], v146 offset:23072
	s_waitcnt vmcnt(8)
	ds_write_b128 v144, v[70:73] offset:36864
	s_waitcnt lgkmcnt(3)
	v_mfma_f32_32x32x16_f16 v[50:65], v[154:157], v[158:161], v[50:65]
	global_load_dwordx4 v[106:109], v137, s[6:7] offset:1920
	s_waitcnt lgkmcnt(2)
	v_mfma_f32_32x32x16_f16 v[34:49], v[162:165], v[158:161], v[34:49]
	ds_read_b128 v[158:161], v146 offset:18496
	s_waitcnt vmcnt(8)
	ds_write_b128 v144, v[74:77] offset:4608
	s_waitcnt lgkmcnt(3)
	v_mfma_f32_32x32x16_f16 v[18:33], v[154:157], v[166:169], v[18:33]
	ds_read_b128 v[154:157], v147 offset:55360
	global_load_dwordx4 v[110:113], v141, s[8:9] offset:1920
	v_mfma_f32_32x32x16_f16 v[2:17], v[162:165], v[166:169], v[2:17]
	ds_read_b128 v[162:165], v147 offset:59968
	ds_read_b128 v[166:169], v146 offset:23104
	s_waitcnt vmcnt(8)
	ds_write_b128 v144, v[78:81] offset:41472
	s_waitcnt lgkmcnt(3)
	v_mfma_f32_32x32x16_f16 v[50:65], v[154:157], v[158:161], v[50:65]
	global_load_dwordx4 v[114:117], v138, s[6:7] offset:1920
	s_waitcnt lgkmcnt(2)
	v_mfma_f32_32x32x16_f16 v[34:49], v[162:165], v[158:161], v[34:49]
	ds_read_b128 v[158:161], v146 offset:18528
	s_waitcnt vmcnt(8)
	ds_write_b128 v144, v[82:85] offset:9216
	s_waitcnt lgkmcnt(3)
	v_mfma_f32_32x32x16_f16 v[18:33], v[154:157], v[166:169], v[18:33]
	ds_read_b128 v[154:157], v147 offset:55392
	global_load_dwordx4 v[118:121], v142, s[8:9] offset:1920
	v_mfma_f32_32x32x16_f16 v[2:17], v[162:165], v[166:169], v[2:17]
	ds_read_b128 v[162:165], v147 offset:60000
	ds_read_b128 v[166:169], v146 offset:23136
	s_waitcnt vmcnt(8)
	ds_write_b128 v144, v[86:89] offset:46080
	s_waitcnt lgkmcnt(3)
	v_mfma_f32_32x32x16_f16 v[50:65], v[154:157], v[158:161], v[50:65]
	global_load_dwordx4 v[122:125], v139, s[6:7] offset:1920
	s_waitcnt lgkmcnt(2)
	v_mfma_f32_32x32x16_f16 v[34:49], v[162:165], v[158:161], v[34:49]
	s_waitcnt vmcnt(8)
	ds_write_b128 v144, v[90:93] offset:13824
	s_waitcnt lgkmcnt(2)
	v_mfma_f32_32x32x16_f16 v[18:33], v[154:157], v[166:169], v[18:33]
	global_load_dwordx4 v[126:129], v143, s[8:9] offset:1920
	v_mfma_f32_32x32x16_f16 v[2:17], v[162:165], v[166:169], v[2:17]
	s_waitcnt vmcnt(8)
	ds_write_b128 v144, v[94:97] offset:50688
	s_setprio 0
	s_waitcnt lgkmcnt(0)
	s_barrier
	s_setprio 1
	ds_read_b128 v[154:157], v147 offset:36864
	ds_read_b128 v[158:161], v146
	ds_read_b128 v[162:165], v147 offset:41472
	ds_read_b128 v[166:169], v146 offset:4608
	s_waitcnt lgkmcnt(2)
	v_mfma_f32_32x32x16_f16 v[50:65], v[154:157], v[158:161], v[50:65]
	s_waitcnt lgkmcnt(1)
	v_mfma_f32_32x32x16_f16 v[34:49], v[162:165], v[158:161], v[34:49]
	ds_read_b128 v[158:161], v146 offset:32
	s_waitcnt vmcnt(7)
	ds_write_b128 v144, v[98:101] offset:18432
	s_waitcnt lgkmcnt(2)
	v_mfma_f32_32x32x16_f16 v[18:33], v[154:157], v[166:169], v[18:33]
	ds_read_b128 v[154:157], v147 offset:36896
	v_mfma_f32_32x32x16_f16 v[2:17], v[162:165], v[166:169], v[2:17]
	ds_read_b128 v[162:165], v147 offset:41504
	ds_read_b128 v[166:169], v146 offset:4640
	s_waitcnt vmcnt(6)
	ds_write_b128 v144, v[102:105] offset:55296
	s_waitcnt lgkmcnt(3)
	v_mfma_f32_32x32x16_f16 v[50:65], v[154:157], v[158:161], v[50:65]
	s_waitcnt lgkmcnt(2)
	v_mfma_f32_32x32x16_f16 v[34:49], v[162:165], v[158:161], v[34:49]
	ds_read_b128 v[158:161], v146 offset:64
	s_waitcnt vmcnt(5)
	ds_write_b128 v144, v[106:109] offset:23040
	s_waitcnt lgkmcnt(3)
	v_mfma_f32_32x32x16_f16 v[18:33], v[154:157], v[166:169], v[18:33]
	ds_read_b128 v[154:157], v147 offset:36928
	v_mfma_f32_32x32x16_f16 v[2:17], v[162:165], v[166:169], v[2:17]
	ds_read_b128 v[162:165], v147 offset:41536
	ds_read_b128 v[166:169], v146 offset:4672
	s_waitcnt vmcnt(4)
	ds_write_b128 v144, v[110:113] offset:59904
	s_waitcnt lgkmcnt(3)
	v_mfma_f32_32x32x16_f16 v[50:65], v[154:157], v[158:161], v[50:65]
	s_waitcnt lgkmcnt(2)
	v_mfma_f32_32x32x16_f16 v[34:49], v[162:165], v[158:161], v[34:49]
	ds_read_b128 v[158:161], v146 offset:96
	s_waitcnt vmcnt(3)
	ds_write_b128 v144, v[114:117] offset:27648
	s_waitcnt lgkmcnt(3)
	v_mfma_f32_32x32x16_f16 v[18:33], v[154:157], v[166:169], v[18:33]
	ds_read_b128 v[154:157], v147 offset:36960
	v_mfma_f32_32x32x16_f16 v[2:17], v[162:165], v[166:169], v[2:17]
	ds_read_b128 v[162:165], v147 offset:41568
	ds_read_b128 v[166:169], v146 offset:4704
	s_waitcnt vmcnt(2)
	ds_write_b128 v144, v[118:121] offset:64512
	s_waitcnt lgkmcnt(3)
	v_mfma_f32_32x32x16_f16 v[50:65], v[154:157], v[158:161], v[50:65]
	s_waitcnt lgkmcnt(2)
	v_mfma_f32_32x32x16_f16 v[34:49], v[162:165], v[158:161], v[34:49]
	s_waitcnt vmcnt(1)
	ds_write_b128 v144, v[122:125] offset:32256
	s_waitcnt lgkmcnt(2)
	v_mfma_f32_32x32x16_f16 v[18:33], v[154:157], v[166:169], v[18:33]
	v_mfma_f32_32x32x16_f16 v[2:17], v[162:165], v[166:169], v[2:17]
	s_waitcnt vmcnt(0)
	ds_write_b128 v145, v[126:129] offset:64512
	s_setprio 0
	s_waitcnt lgkmcnt(0)
	s_barrier
; DI void phase5(const Params& p, int l, const float* xin, float* xout, char* lds) {
;     ...
; #pragma unroll
;     for (int mi = 0; mi < 2; ++mi) {
;       const size_t row = (size_t)mt * 128 + wm * 64 + mi * 32 + r;
; #pragma unroll
;       for (int ni = 0; ni < 2; ++ni)
; #pragma unroll
;         for (int a = 0; a < 4; ++a) {
;           const int col = nt * 128 + wn * 64 + ni * 32 + 8 * a + 4 * h;
;           float4 xv = *(const float4*)(xin + row * 1024 + col);
;           xv.x += acc[mi][ni][4 * a];
;           xv.y += acc[mi][ni][4 * a + 1];
;           xv.z += acc[mi][ni][4 * a + 2];
;           xv.w += acc[mi][ni][4 * a + 3];
;           *(float4*)(xout + row * 1024 + col) = xv;
;         }
	s_setprio 1
	ds_read_b128 v[154:157], v147 offset:55296
	ds_read_b128 v[158:161], v146 offset:18432
	ds_read_b128 v[162:165], v147 offset:59904
	ds_read_b128 v[166:169], v146 offset:23040
	s_waitcnt lgkmcnt(2)
	v_mfma_f32_32x32x16_f16 v[50:65], v[154:157], v[158:161], v[50:65]
	s_waitcnt lgkmcnt(1)
	v_mfma_f32_32x32x16_f16 v[34:49], v[162:165], v[158:161], v[34:49]
	ds_read_b128 v[158:161], v146 offset:18464
	s_waitcnt lgkmcnt(1)
	v_mfma_f32_32x32x16_f16 v[18:33], v[154:157], v[166:169], v[18:33]
	ds_read_b128 v[154:157], v147 offset:55328
	v_mfma_f32_32x32x16_f16 v[2:17], v[162:165], v[166:169], v[2:17]
	ds_read_b128 v[162:165], v147 offset:59936
	ds_read_b128 v[166:169], v146 offset:23072
	s_waitcnt lgkmcnt(2)
	v_mfma_f32_32x32x16_f16 v[50:65], v[154:157], v[158:161], v[50:65]
	s_waitcnt lgkmcnt(1)
	v_mfma_f32_32x32x16_f16 v[34:49], v[162:165], v[158:161], v[34:49]
	ds_read_b128 v[158:161], v146 offset:18496
	s_waitcnt lgkmcnt(1)
	v_mfma_f32_32x32x16_f16 v[18:33], v[154:157], v[166:169], v[18:33]
	ds_read_b128 v[154:157], v147 offset:55360
	v_mfma_f32_32x32x16_f16 v[2:17], v[162:165], v[166:169], v[2:17]
	ds_read_b128 v[162:165], v147 offset:59968
	ds_read_b128 v[166:169], v146 offset:23104
	s_waitcnt lgkmcnt(2)
	v_mfma_f32_32x32x16_f16 v[50:65], v[154:157], v[158:161], v[50:65]
	s_waitcnt lgkmcnt(1)
	v_mfma_f32_32x32x16_f16 v[34:49], v[162:165], v[158:161], v[34:49]
	ds_read_b128 v[158:161], v146 offset:18528
	s_waitcnt lgkmcnt(1)
	v_mfma_f32_32x32x16_f16 v[18:33], v[154:157], v[166:169], v[18:33]
	ds_read_b128 v[154:157], v147 offset:55392
	v_mfma_f32_32x32x16_f16 v[2:17], v[162:165], v[166:169], v[2:17]
	ds_read_b128 v[162:165], v147 offset:60000
	ds_read_b128 v[166:169], v146 offset:23136
	s_waitcnt lgkmcnt(2)
	v_mfma_f32_32x32x16_f16 v[50:65], v[154:157], v[158:161], v[50:65]
	s_waitcnt lgkmcnt(1)
	v_mfma_f32_32x32x16_f16 v[34:49], v[162:165], v[158:161], v[34:49]
	s_waitcnt lgkmcnt(0)
	v_mfma_f32_32x32x16_f16 v[18:33], v[154:157], v[166:169], v[18:33]
	v_mfma_f32_32x32x16_f16 v[2:17], v[162:165], v[166:169], v[2:17]
	s_setprio 0
	s_nop 1
	s_barrier
	v_and_b32_e32 v66, 63, v209
	v_lshrrev_b32_e32 v67, 4, v66
	v_and_b32_e32 v68, 15, v66
	v_lshrrev_b32_e32 v69, 7, v209
	v_lshl_add_u32 v69, v69, 6, v67
	s_lshl_b32 s6, s0, 7
	v_add_u32_e32 v69, s6, v69
	v_lshlrev_b32_e32 v70, 12, v69
	s_lshl_b32 s6, s5, 9
	v_and_b32_e32 v71, 64, v209
	v_lshl_add_u32 v70, v71, 2, v70
	v_lshl_add_u32 v70, v68, 4, v70
	v_add_u32_e32 v72, s6, v70
	v_mov_b32_e32 v73, v72
	v_lshrrev_b32_e32 v74, 6, v209
	v_mul_u32_u24_e32 v76, 0x2400, v74
	v_lshrrev_b32_e32 v74, 1, v74
	v_mul_u32_u24_e32 v74, 0x4800, v74
	v_add_u32_e32 v76, v76, v74
	v_add_u32_e32 v76, 0x4800, v76
	v_and_b32_e32 v75, 31, v66
	v_lshrrev_b32_e32 v74, 5, v66
	v_mul_u32_u24_e32 v75, 0x110, v75
	v_lshl_add_u32 v75, v74, 4, v75
	v_add_u32_e32 v75, v75, v76
	v_mul_u32_u24_e32 v77, 0x110, v67
	v_lshl_add_u32 v77, v68, 4, v77
	v_add_u32_e32 v77, v77, v76
	global_load_dwordx4 v[84:87], v72, s[12:13]
	v_add_u32_e32 v72, 0x4000, v72
	global_load_dwordx4 v[88:91], v72, s[12:13]
	v_add_u32_e32 v72, 0x4000, v72
	global_load_dwordx4 v[92:95], v72, s[12:13]
	v_add_u32_e32 v72, 0x4000, v72
	global_load_dwordx4 v[96:99], v72, s[12:13]
	v_add_u32_e32 v72, 0x4000, v72
	global_load_dwordx4 v[100:103], v72, s[12:13]
	v_add_u32_e32 v72, 0x4000, v72
	global_load_dwordx4 v[104:107], v72, s[12:13]
	v_add_u32_e32 v72, 0x4000, v72
	global_load_dwordx4 v[108:111], v72, s[12:13]
	v_add_u32_e32 v72, 0x4000, v72
	global_load_dwordx4 v[112:115], v72, s[12:13]
	v_add_u32_e32 v72, 0x4000, v72
	ds_write_b128 v75, v[50:53]
	ds_write_b128 v75, v[54:57] offset:32
	ds_write_b128 v75, v[58:61] offset:64
	ds_write_b128 v75, v[62:65] offset:96
	ds_write_b128 v75, v[34:37] offset:128
	ds_write_b128 v75, v[38:41] offset:160
	ds_write_b128 v75, v[42:45] offset:192
	ds_write_b128 v75, v[46:49] offset:224
	s_waitcnt lgkmcnt(0)
	ds_read_b128 v[34:37], v77
	ds_read_b128 v[38:41], v77 offset:1088
	ds_read_b128 v[42:45], v77 offset:2176
	ds_read_b128 v[46:49], v77 offset:3264
	ds_read_b128 v[50:53], v77 offset:4352
	ds_read_b128 v[54:57], v77 offset:5440
	ds_read_b128 v[58:61], v77 offset:6528
	ds_read_b128 v[62:65], v77 offset:7616
	s_waitcnt vmcnt(7) lgkmcnt(7)
	v_pk_add_f32 v[34:35], v[34:35], v[84:85]
	v_pk_add_f32 v[36:37], v[36:37], v[86:87]
	global_store_dwordx4 v73, v[34:37], s[10:11]
	v_add_u32_e32 v73, 0x4000, v73
	s_waitcnt vmcnt(7) lgkmcnt(6)
	v_pk_add_f32 v[38:39], v[38:39], v[88:89]
	v_pk_add_f32 v[40:41], v[40:41], v[90:91]
	global_store_dwordx4 v73, v[38:41], s[10:11]
	v_add_u32_e32 v73, 0x4000, v73
	s_waitcnt vmcnt(7) lgkmcnt(5)
; DI void phase5(const Params& p, int l, const float* xin, float* xout, char* lds) {
;     ...
; #pragma unroll
;     for (int mi = 0; mi < 2; ++mi) {
;       const size_t row = (size_t)mt * 128 + wm * 64 + mi * 32 + r;
; #pragma unroll
;       for (int ni = 0; ni < 2; ++ni)
; #pragma unroll
;         for (int a = 0; a < 4; ++a) {
;           const int col = nt * 128 + wn * 64 + ni * 32 + 8 * a + 4 * h;
;           float4 xv = *(const float4*)(xin + row * 1024 + col);
;           xv.x += acc[mi][ni][4 * a];
;           xv.y += acc[mi][ni][4 * a + 1];
;           xv.z += acc[mi][ni][4 * a + 2];
;           xv.w += acc[mi][ni][4 * a + 3];
;           *(float4*)(xout + row * 1024 + col) = xv;
;         }
;     }
;   }
; }
	v_pk_add_f32 v[42:43], v[42:43], v[92:93]
	v_pk_add_f32 v[44:45], v[44:45], v[94:95]
	global_store_dwordx4 v73, v[42:45], s[10:11]
	v_add_u32_e32 v73, 0x4000, v73
	s_waitcnt vmcnt(7) lgkmcnt(4)
	v_pk_add_f32 v[46:47], v[46:47], v[96:97]
	v_pk_add_f32 v[48:49], v[48:49], v[98:99]
	global_store_dwordx4 v73, v[46:49], s[10:11]
	v_add_u32_e32 v73, 0x4000, v73
	s_waitcnt vmcnt(7) lgkmcnt(3)
	v_pk_add_f32 v[50:51], v[50:51], v[100:101]
	v_pk_add_f32 v[52:53], v[52:53], v[102:103]
	global_store_dwordx4 v73, v[50:53], s[10:11]
	v_add_u32_e32 v73, 0x4000, v73
	s_waitcnt vmcnt(7) lgkmcnt(2)
	v_pk_add_f32 v[54:55], v[54:55], v[104:105]
	v_pk_add_f32 v[56:57], v[56:57], v[106:107]
	global_store_dwordx4 v73, v[54:57], s[10:11]
	v_add_u32_e32 v73, 0x4000, v73
	s_waitcnt vmcnt(7) lgkmcnt(1)
	v_pk_add_f32 v[58:59], v[58:59], v[108:109]
	v_pk_add_f32 v[60:61], v[60:61], v[110:111]
	global_store_dwordx4 v73, v[58:61], s[10:11]
	v_add_u32_e32 v73, 0x4000, v73
	s_waitcnt vmcnt(7) lgkmcnt(0)
	v_pk_add_f32 v[62:63], v[62:63], v[112:113]
	v_pk_add_f32 v[64:65], v[64:65], v[114:115]
	global_store_dwordx4 v73, v[62:65], s[10:11]
	v_add_u32_e32 v73, 0x4000, v73
	global_load_dwordx4 v[84:87], v72, s[12:13]
	v_add_u32_e32 v72, 0x4000, v72
	global_load_dwordx4 v[88:91], v72, s[12:13]
	v_add_u32_e32 v72, 0x4000, v72
	global_load_dwordx4 v[92:95], v72, s[12:13]
	v_add_u32_e32 v72, 0x4000, v72
	global_load_dwordx4 v[96:99], v72, s[12:13]
	v_add_u32_e32 v72, 0x4000, v72
	global_load_dwordx4 v[100:103], v72, s[12:13]
	v_add_u32_e32 v72, 0x4000, v72
	global_load_dwordx4 v[104:107], v72, s[12:13]
	v_add_u32_e32 v72, 0x4000, v72
	global_load_dwordx4 v[108:111], v72, s[12:13]
	v_add_u32_e32 v72, 0x4000, v72
	global_load_dwordx4 v[112:115], v72, s[12:13]
	v_add_u32_e32 v72, 0x4000, v72
	ds_write_b128 v75, v[18:21]
	ds_write_b128 v75, v[22:25] offset:32
	ds_write_b128 v75, v[26:29] offset:64
	ds_write_b128 v75, v[30:33] offset:96
	ds_write_b128 v75, v[2:5] offset:128
	ds_write_b128 v75, v[6:9] offset:160
	ds_write_b128 v75, v[10:13] offset:192
	ds_write_b128 v75, v[14:17] offset:224
	s_waitcnt lgkmcnt(0)
	ds_read_b128 v[2:5], v77
	ds_read_b128 v[6:9], v77 offset:1088
	ds_read_b128 v[10:13], v77 offset:2176
	ds_read_b128 v[14:17], v77 offset:3264
	ds_read_b128 v[18:21], v77 offset:4352
	ds_read_b128 v[22:25], v77 offset:5440
	ds_read_b128 v[26:29], v77 offset:6528
	ds_read_b128 v[30:33], v77 offset:7616
	s_waitcnt vmcnt(7) lgkmcnt(7)
	v_pk_add_f32 v[2:3], v[2:3], v[84:85]
	v_pk_add_f32 v[4:5], v[4:5], v[86:87]
	global_store_dwordx4 v73, v[2:5], s[10:11]
	v_add_u32_e32 v73, 0x4000, v73
	s_waitcnt vmcnt(7) lgkmcnt(6)
	v_pk_add_f32 v[6:7], v[6:7], v[88:89]
	v_pk_add_f32 v[8:9], v[8:9], v[90:91]
	global_store_dwordx4 v73, v[6:9], s[10:11]
	v_add_u32_e32 v73, 0x4000, v73
	s_waitcnt vmcnt(7) lgkmcnt(5)
	v_pk_add_f32 v[10:11], v[10:11], v[92:93]
	v_pk_add_f32 v[12:13], v[12:13], v[94:95]
	global_store_dwordx4 v73, v[10:13], s[10:11]
	v_add_u32_e32 v73, 0x4000, v73
	s_waitcnt vmcnt(7) lgkmcnt(4)
	v_pk_add_f32 v[14:15], v[14:15], v[96:97]
	v_pk_add_f32 v[16:17], v[16:17], v[98:99]
	global_store_dwordx4 v73, v[14:17], s[10:11]
	v_add_u32_e32 v73, 0x4000, v73
	s_waitcnt vmcnt(7) lgkmcnt(3)
	v_pk_add_f32 v[18:19], v[18:19], v[100:101]
	v_pk_add_f32 v[20:21], v[20:21], v[102:103]
	global_store_dwordx4 v73, v[18:21], s[10:11]
	v_add_u32_e32 v73, 0x4000, v73
	s_waitcnt vmcnt(7) lgkmcnt(2)
	v_pk_add_f32 v[22:23], v[22:23], v[104:105]
	v_pk_add_f32 v[24:25], v[24:25], v[106:107]
	global_store_dwordx4 v73, v[22:25], s[10:11]
	v_add_u32_e32 v73, 0x4000, v73
	s_waitcnt vmcnt(7) lgkmcnt(1)
	v_pk_add_f32 v[26:27], v[26:27], v[108:109]
	v_pk_add_f32 v[28:29], v[28:29], v[110:111]
	global_store_dwordx4 v73, v[26:29], s[10:11]
	v_add_u32_e32 v73, 0x4000, v73
	s_waitcnt vmcnt(7) lgkmcnt(0)
	v_pk_add_f32 v[30:31], v[30:31], v[112:113]
	v_pk_add_f32 v[32:33], v[32:33], v[114:115]
	global_store_dwordx4 v73, v[30:33], s[10:11]
	v_add_u32_e32 v73, 0x4000, v73
	s_add_i32 s4, s4, s30
	s_cmpk_lt_i32 s4, 0x400
	s_cbranch_scc1 .LBB0_1116
	v_readlane_b32 s0, v253, 1
	v_readlane_b32 s1, v253, 2
	v_lshlrev_b32_e32 v66, 4, v209
	s_nop 4
	global_load_dwordx4 v[166:169], v66, s[0:1]
	v_add_u32_e32 v66, 0x1000, v66
	global_load_dwordx4 v[170:173], v66, s[0:1]
	v_add_u32_e32 v66, 0x1000, v66
	global_load_dwordx4 v[174:177], v66, s[0:1]
	v_add_u32_e32 v66, 0x1000, v66
	global_load_dwordx4 v[178:181], v66, s[0:1]
	v_add_u32_e32 v66, 0x1000, v66
	global_load_dwordx4 v[182:185], v66, s[0:1]
	v_add_u32_e32 v66, 0x1000, v66
	s_waitcnt vmcnt(0)
	s_mov_b32 s19, s25
